# v21 plus: EpiGate, the 15 x/bias loads of groups 2-4 issued at the epilogue start into dead registers (one load round trip per unit instead of four); later groups' load waits removed
# speedup vs baseline: 1.0013x; 1.0013x over previous
;     __device__ __forceinline__ void operator()(const f32x4 (&acc)[2][2][4][2], const Unit& u, int wr, int wc, int fr, int fq) const {
;         const int row0 = u.pm * 256 + wr * 64 + fr, ch0 = u.pn * 128 + wc * 32 + 4 * fq;
; #pragma unroll
;         for (int n = 0; n < 2; ++n) { const f32x4 ba = *(const f32x4*)(bga + ch0 + 16 * n), bx = *(const f32x4*)(bgx + ch0 + 16 * n), lv = *(const f32x4*)(ll + ch0 + 16 * n);
; #pragma unroll
;             for (int ai = 0; ai < 2; ++ai) { u32x2 xq[4];
; #pragma unroll
;                 for (int m = 0; m < 4; ++m) { const int row = row0 + ai * 128 + m * 16; xq[m] = *(const u32x2*)(XC + (size_t)(row < TT ? row : TT - 1) * DRNN + ch0 + 16 * n); }
.LBB0_759:
	v_lshl_add_u32 v196, s11, 8, v174
	v_lshl_or_b32 v146, s6, 7, v191
	v_ashrrev_i32_e32 v147, 31, v146
	v_or_b32_e32 v195, 16, v196
	v_or_b32_e32 v194, 32, v196
	v_or_b32_e32 v193, 48, v196
	v_lshlrev_b64 v[92:93], 2, v[146:147]
	v_lshl_add_u64 v[148:149], v[146:147], 1, s[26:27]
	v_min_i32_e32 v158, 0x207f, v195
	v_min_i32_e32 v160, 0x207f, v194
	v_min_i32_e32 v162, 0x207f, v193
	v_lshl_add_u64 v[152:153], s[64:65], 0, v[92:93]
	v_lshl_add_u64 v[154:155], s[66:67], 0, v[92:93]
	v_lshl_add_u64 v[156:157], s[68:69], 0, v[92:93]
	v_mad_i64_i32 v[158:159], s[22:23], v158, s91, v[148:149]
	v_mad_i64_i32 v[160:161], s[22:23], v160, s91, v[148:149]
	v_mad_i64_i32 v[162:163], s[22:23], v162, s91, v[148:149]
	global_load_dwordx4 v[96:99], v[152:153], off
	global_load_dwordx4 v[88:91], v[154:155], off
	global_load_dwordx4 v[92:95], v[156:157], off
	global_load_dwordx2 v[168:169], v[158:159], off
	global_load_dwordx2 v[166:167], v[160:161], off
	global_load_dwordx2 v[164:165], v[162:163], off
	v_min_i32_e32 v150, 0x207f, v196
	s_movk_i32 s6, 0x2080
	v_mad_i64_i32 v[150:151], s[22:23], v150, s91, 0
	v_cmp_gt_i32_e32 vcc, s6, v196
	v_add_u32_e32 v208, 0x90, v196
	v_add_u32_e32 v210, 0xa0, v196
	v_add_u32_e32 v212, 0xb0, v196
	v_add_u32_e32 v224, 0x80, v196
	v_min_i32_e32 v208, 0x207f, v208
	v_min_i32_e32 v210, 0x207f, v210
	v_min_i32_e32 v212, 0x207f, v212
	v_min_i32_e32 v224, 0x207f, v224
	v_mad_i64_i32 v[208:209], s[22:23], v208, s91, v[148:149]
	v_mad_i64_i32 v[210:211], s[22:23], v210, s91, v[148:149]
	v_mad_i64_i32 v[212:213], s[22:23], v212, s91, v[148:149]
	v_mad_i64_i32 v[224:225], s[22:23], v224, s91, v[148:149]
	global_load_dwordx2 v[202:203], v[208:209], off
	global_load_dwordx2 v[204:205], v[210:211], off
	global_load_dwordx2 v[206:207], v[212:213], off
	global_load_dwordx2 v[200:201], v[224:225], off
	global_load_dwordx2 v[208:209], v[208:209], off offset:32
	global_load_dwordx2 v[210:211], v[210:211], off offset:32
	global_load_dwordx2 v[212:213], v[212:213], off offset:32
	global_load_dwordx2 v[224:225], v[224:225], off offset:32
	global_load_dwordx4 v[226:229], v[152:153], off offset:64
	global_load_dwordx4 v[230:233], v[154:155], off offset:64
	global_load_dwordx4 v[234:237], v[156:157], off offset:64
	global_load_dwordx2 v[238:239], v[158:159], off offset:32
	global_load_dwordx2 v[240:241], v[160:161], off offset:32
	global_load_dwordx2 v[242:243], v[162:163], off offset:32
	v_lshl_add_u64 v[244:245], v[148:149], 0, v[150:151]
	global_load_dwordx2 v[244:245], v[244:245], off offset:32
	s_and_saveexec_b64 s[22:23], vcc
	s_cbranch_execnz .LBB0_763
	s_or_b64 exec, exec, s[22:23]
	v_cmp_gt_i32_e64 s[42:43], s6, v195
	s_and_saveexec_b64 s[22:23], s[42:43]
	s_cbranch_execnz .LBB0_780

; __device__ __forceinline__ unsigned cvt_pk_bf16(float lo, float hi) { unsigned r; asm volatile("v_cvt_pk_bf16_f32 %0, %1, %2" : "=v"(r) : "v"(lo), "v"(hi)); return r; }
; __device__ __forceinline__ float bflo(unsigned w) { return __uint_as_float(w << 16); }
; __device__ __forceinline__ float bfhi(unsigned w) { return __uint_as_float(w & 0xffff0000u); }
; __device__ __forceinline__ float fsigmoid(float x) { return __builtin_amdgcn_rcpf(1.0f + __expf(-x)); }
;     __device__ __forceinline__ void operator()(const f32x4 (&acc)[2][2][4][2], const Unit& u, int wr, int wc, int fr, int fq) const {
;     ...
;                 for (int m = 0; m < 4; ++m) { const int row = row0 + ai * 128 + m * 16;
;                     if (row < TT) { const size_t off = (size_t)row * DRNN + ch0 + 16 * n; const u32x2 xw = xq[m]; const f32x4 xc = (f32x4){bflo(xw.x), bfhi(xw.x), bflo(xw.y), bfhi(xw.y)}; u32x4 o;
; #pragma unroll
;                         for (int i = 0; i < 4; ++i) { const float r = fsigmoid(acc[ai][0][m][n][i] + ba[i]), ig = fsigmoid(acc[ai][1][m][n][i] + bx[i]);
;                             const float la = r * lv[i], x2 = la + la, m = x2 > -1e-3f ? -x2 * fmaf(x2, 0.5f, 1.0f) : 1.0f - __expf(x2);
;                             o[i] = cvt_pk_bf16(la, __builtin_amdgcn_sqrtf(fmaxf(m, 0.0f)) * ig * xc[i]); }
;                         *(u32x4*)(AB + off) = o; } }
.LBB0_831:
	s_or_b64 exec, exec, s[22:23]
	v_add_u32_e32 v126, 0x90, v196
	v_add_u32_e32 v125, 0xa0, v196
	v_add_u32_e32 v124, 0xb0, v196
	v_add_u32_e32 v127, 0x80, v196
	v_cmp_gt_i32_e64 s[48:49], s89, v196
	s_and_saveexec_b64 s[22:23], s[48:49]
	s_cbranch_execz .LBB0_849
	v_add_f32_e32 v104, v104, v96
	v_mul_f32_e32 v104, 0xbfb8aa3b, v104
	v_exp_f32_e32 v104, v104
	s_nop 0
	v_add_f32_e32 v104, 1.0, v104
	v_rcp_f32_e32 v104, v104
	s_nop 0
	v_mul_f32_e32 v104, v92, v104
	v_add_f32_e32 v129, v104, v104
	v_cmp_nlt_f32_e64 s[50:51], s95, v129
	s_and_saveexec_b64 s[34:35], s[50:51]
	s_xor_b64 s[36:37], exec, s[34:35]
	v_mul_f32_e32 v128, 0x3fb8aa3b, v129
	v_exp_f32_e32 v128, v128
	s_nop 0
	v_sub_f32_e32 v128, 1.0, v128
	s_andn2_saveexec_b64 s[36:37], s[36:37]
	v_fma_f32 v128, v129, 0.5, 1.0
	v_mul_f32_e64 v128, v128, -v129
	s_or_b64 exec, exec, s[36:37]
	v_add_f32_e32 v100, v100, v88
	v_mul_f32_e32 v100, 0xbfb8aa3b, v100
	v_exp_f32_e32 v100, v100
	v_add_f32_e32 v105, v105, v97
	v_mul_f32_e32 v105, 0xbfb8aa3b, v105
	v_exp_f32_e32 v105, v105
	v_max_f32_e32 v128, v128, v128
	v_add_f32_e32 v100, 1.0, v100
	v_max_f32_e32 v128, 0, v128
	v_rcp_f32_e32 v100, v100
	v_sqrt_f32_e32 v128, v128
	v_add_f32_e32 v105, 1.0, v105
	v_rcp_f32_e32 v105, v105
	v_lshlrev_b32_e32 v129, 16, v200
	v_mul_f32_e32 v100, v100, v128
	v_mul_f32_e32 v100, v100, v129
	v_cvt_pk_bf16_f32 v100, v104, v100
	v_mul_f32_e32 v104, v93, v105
	v_add_f32_e32 v128, v104, v104
	v_cmp_nlt_f32_e64 s[50:51], s95, v128
	s_and_saveexec_b64 s[34:35], s[50:51]
	s_xor_b64 s[36:37], exec, s[34:35]
	v_mul_f32_e32 v105, 0x3fb8aa3b, v128
	v_exp_f32_e32 v105, v105
	s_nop 0
	v_sub_f32_e32 v105, 1.0, v105
	s_andn2_saveexec_b64 s[36:37], s[36:37]
	v_fma_f32 v105, v128, 0.5, 1.0
	v_mul_f32_e64 v105, v105, -v128
	s_or_b64 exec, exec, s[36:37]
	v_add_f32_e32 v101, v101, v89
	v_mul_f32_e32 v101, 0xbfb8aa3b, v101
	v_exp_f32_e32 v101, v101
	v_add_f32_e32 v106, v106, v98
	v_mul_f32_e32 v106, 0xbfb8aa3b, v106
	v_exp_f32_e32 v106, v106
	v_max_f32_e32 v105, v105, v105
	v_add_f32_e32 v101, 1.0, v101
	v_max_f32_e32 v105, 0, v105
	v_rcp_f32_e32 v101, v101
	v_sqrt_f32_e32 v105, v105
	v_add_f32_e32 v106, 1.0, v106
	v_rcp_f32_e32 v106, v106
	v_and_b32_e32 v200, 0xffff0000, v200
	v_mul_f32_e32 v101, v101, v105
	v_mul_f32_e32 v101, v101, v200
	v_cvt_pk_bf16_f32 v101, v104, v101
	v_mul_f32_e32 v104, v94, v106
	v_add_f32_e32 v106, v104, v104
	v_cmp_nlt_f32_e64 s[50:51], s95, v106
	s_and_saveexec_b64 s[34:35], s[50:51]
	s_xor_b64 s[36:37], exec, s[34:35]
	v_mul_f32_e32 v105, 0x3fb8aa3b, v106
	v_exp_f32_e32 v105, v105
	s_nop 0
	v_sub_f32_e32 v105, 1.0, v105
	s_andn2_saveexec_b64 s[36:37], s[36:37]
	v_fma_f32 v105, v106, 0.5, 1.0
	v_mul_f32_e64 v105, v105, -v106
	s_or_b64 exec, exec, s[36:37]
	v_add_f32_e32 v102, v102, v90
	v_mul_f32_e32 v102, 0xbfb8aa3b, v102
	v_exp_f32_e32 v102, v102
	v_add_f32_e32 v106, v107, v99
	v_mul_f32_e32 v106, 0xbfb8aa3b, v106
	v_exp_f32_e32 v106, v106
	v_max_f32_e32 v105, v105, v105
	v_add_f32_e32 v102, 1.0, v102
	v_max_f32_e32 v105, 0, v105
	v_rcp_f32_e32 v102, v102
	v_sqrt_f32_e32 v105, v105
	v_add_f32_e32 v106, 1.0, v106
	v_rcp_f32_e32 v106, v106
	v_lshlrev_b32_e32 v107, 16, v201
	v_mul_f32_e32 v102, v102, v105
	v_mul_f32_e32 v102, v102, v107
	v_cvt_pk_bf16_f32 v102, v104, v102
	v_mul_f32_e32 v104, v95, v106
	v_add_f32_e32 v106, v104, v104
	v_cmp_nlt_f32_e64 s[50:51], s95, v106
	s_and_saveexec_b64 s[34:35], s[50:51]
	s_xor_b64 s[36:37], exec, s[34:35]
	v_mul_f32_e32 v105, 0x3fb8aa3b, v106
	v_exp_f32_e32 v105, v105
	s_nop 0
	v_sub_f32_e32 v105, 1.0, v105
	s_andn2_saveexec_b64 s[36:37], s[36:37]
	v_fma_f32 v105, v106, 0.5, 1.0
	v_mul_f32_e64 v105, v105, -v106
	s_or_b64 exec, exec, s[36:37]
	v_add_f32_e32 v103, v103, v91
	v_mul_f32_e32 v103, 0xbfb8aa3b, v103
	v_exp_f32_e32 v103, v103
	v_max_f32_e32 v105, v105, v105
	v_max_f32_e32 v105, 0, v105
	v_sqrt_f32_e32 v105, v105
	v_add_f32_e32 v103, 1.0, v103
	v_rcp_f32_e32 v103, v103
	v_and_b32_e32 v106, 0xffff0000, v201
	v_mul_f32_e32 v103, v103, v105
	v_mul_f32_e32 v103, v103, v106
	v_cvt_pk_bf16_f32 v103, v104, v103
	v_mov_b64_e32 v[104:105], s[62:63]
	v_mad_i64_i32 v[104:105], s[34:35], v127, s87, v[104:105]
	v_lshl_add_u64 v[104:105], v[146:147], 2, v[104:105]
	global_store_dwordx4 v[104:105], v[100:103], off
; __device__ __forceinline__ unsigned cvt_pk_bf16(float lo, float hi) { unsigned r; asm volatile("v_cvt_pk_bf16_f32 %0, %1, %2" : "=v"(r) : "v"(lo), "v"(hi)); return r; }
; __device__ __forceinline__ float bflo(unsigned w) { return __uint_as_float(w << 16); }
; __device__ __forceinline__ float bfhi(unsigned w) { return __uint_as_float(w & 0xffff0000u); }
; __device__ __forceinline__ float fsigmoid(float x) { return __builtin_amdgcn_rcpf(1.0f + __expf(-x)); }
;     __device__ __forceinline__ void operator()(const f32x4 (&acc)[2][2][4][2], const Unit& u, int wr, int wc, int fr, int fq) const {
;     ...
;                 for (int m = 0; m < 4; ++m) { const int row = row0 + ai * 128 + m * 16;
;                     if (row < TT) { const size_t off = (size_t)row * DRNN + ch0 + 16 * n; const u32x2 xw = xq[m]; const f32x4 xc = (f32x4){bflo(xw.x), bfhi(xw.x), bflo(xw.y), bfhi(xw.y)}; u32x4 o;
; #pragma unroll
;                         for (int i = 0; i < 4; ++i) { const float r = fsigmoid(acc[ai][0][m][n][i] + ba[i]), ig = fsigmoid(acc[ai][1][m][n][i] + bx[i]);
;                             const float la = r * lv[i], x2 = la + la, m = x2 > -1e-3f ? -x2 * fmaf(x2, 0.5f, 1.0f) : 1.0f - __expf(x2);
;                             o[i] = cvt_pk_bf16(la, __builtin_amdgcn_sqrtf(fmaxf(m, 0.0f)) * ig * xc[i]); }
;                         *(u32x4*)(AB + off) = o; } }
.LBB0_849:
	s_or_b64 exec, exec, s[22:23]
	s_movk_i32 s6, 0x1ff0
	v_cmp_gt_i32_e64 s[50:51], s6, v196
	s_and_saveexec_b64 s[22:23], s[50:51]
	s_cbranch_execz .LBB0_867
	v_add_f32_e32 v84, v84, v96
	v_mul_f32_e32 v84, 0xbfb8aa3b, v84
	v_exp_f32_e32 v84, v84
	s_nop 0
	v_add_f32_e32 v84, 1.0, v84
	v_rcp_f32_e32 v84, v84
	s_nop 0
	v_mul_f32_e32 v84, v92, v84
	v_add_f32_e32 v101, v84, v84
	v_cmp_nlt_f32_e64 s[52:53], s95, v101
	s_and_saveexec_b64 s[34:35], s[52:53]
	s_xor_b64 s[36:37], exec, s[34:35]
	v_mul_f32_e32 v100, 0x3fb8aa3b, v101
	v_exp_f32_e32 v100, v100
	s_nop 0
	v_sub_f32_e32 v100, 1.0, v100
	s_andn2_saveexec_b64 s[36:37], s[36:37]
	v_fma_f32 v100, v101, 0.5, 1.0
	v_mul_f32_e64 v100, v100, -v101
	s_or_b64 exec, exec, s[36:37]
	v_add_f32_e32 v80, v80, v88
	v_mul_f32_e32 v80, 0xbfb8aa3b, v80
	v_exp_f32_e32 v80, v80
	v_add_f32_e32 v85, v85, v97
	v_mul_f32_e32 v85, 0xbfb8aa3b, v85
	v_exp_f32_e32 v85, v85
	v_max_f32_e32 v100, v100, v100
	v_add_f32_e32 v80, 1.0, v80
	v_max_f32_e32 v100, 0, v100
	v_rcp_f32_e32 v80, v80
	v_sqrt_f32_e32 v100, v100
	v_add_f32_e32 v85, 1.0, v85
	v_rcp_f32_e32 v85, v85
	v_lshlrev_b32_e32 v101, 16, v202
	v_mul_f32_e32 v80, v80, v100
	v_mul_f32_e32 v80, v80, v101
	v_cvt_pk_bf16_f32 v80, v84, v80
	v_mul_f32_e32 v84, v93, v85
	v_add_f32_e32 v100, v84, v84
	v_cmp_nlt_f32_e64 s[52:53], s95, v100
	s_and_saveexec_b64 s[34:35], s[52:53]
	s_xor_b64 s[36:37], exec, s[34:35]
	v_mul_f32_e32 v85, 0x3fb8aa3b, v100
	v_exp_f32_e32 v85, v85
	s_nop 0
	v_sub_f32_e32 v85, 1.0, v85
	s_andn2_saveexec_b64 s[36:37], s[36:37]
	v_fma_f32 v85, v100, 0.5, 1.0
	v_mul_f32_e64 v85, v85, -v100
	s_or_b64 exec, exec, s[36:37]
	v_add_f32_e32 v81, v81, v89
	v_mul_f32_e32 v81, 0xbfb8aa3b, v81
	v_exp_f32_e32 v81, v81
	v_add_f32_e32 v86, v86, v98
	v_mul_f32_e32 v86, 0xbfb8aa3b, v86
	v_exp_f32_e32 v86, v86
	v_max_f32_e32 v85, v85, v85
	v_add_f32_e32 v81, 1.0, v81
	v_max_f32_e32 v85, 0, v85
	v_rcp_f32_e32 v81, v81
	v_sqrt_f32_e32 v85, v85
	v_add_f32_e32 v86, 1.0, v86
	v_rcp_f32_e32 v86, v86
	v_and_b32_e32 v100, 0xffff0000, v202
	v_mul_f32_e32 v81, v81, v85
	v_mul_f32_e32 v81, v81, v100
	v_cvt_pk_bf16_f32 v81, v84, v81
	v_mul_f32_e32 v84, v94, v86
	v_add_f32_e32 v86, v84, v84
	v_cmp_nlt_f32_e64 s[52:53], s95, v86
	s_and_saveexec_b64 s[34:35], s[52:53]
	s_xor_b64 s[36:37], exec, s[34:35]
	v_mul_f32_e32 v85, 0x3fb8aa3b, v86
	v_exp_f32_e32 v85, v85
	s_nop 0
	v_sub_f32_e32 v85, 1.0, v85
	s_andn2_saveexec_b64 s[36:37], s[36:37]
	v_fma_f32 v85, v86, 0.5, 1.0
	v_mul_f32_e64 v85, v85, -v86
	s_or_b64 exec, exec, s[36:37]
	v_add_f32_e32 v82, v82, v90
	v_mul_f32_e32 v82, 0xbfb8aa3b, v82
	v_exp_f32_e32 v82, v82
	v_add_f32_e32 v86, v87, v99
	v_mul_f32_e32 v86, 0xbfb8aa3b, v86
	v_exp_f32_e32 v86, v86
	v_max_f32_e32 v85, v85, v85
	v_add_f32_e32 v82, 1.0, v82
	v_max_f32_e32 v85, 0, v85
	v_rcp_f32_e32 v82, v82
	v_sqrt_f32_e32 v85, v85
	v_add_f32_e32 v86, 1.0, v86
	v_rcp_f32_e32 v86, v86
	v_lshlrev_b32_e32 v87, 16, v203
	v_mul_f32_e32 v82, v82, v85
	v_mul_f32_e32 v82, v82, v87
	v_cvt_pk_bf16_f32 v82, v84, v82
	v_mul_f32_e32 v84, v95, v86
	v_add_f32_e32 v86, v84, v84
	v_cmp_nlt_f32_e64 s[52:53], s95, v86
	s_and_saveexec_b64 s[34:35], s[52:53]
	s_xor_b64 s[36:37], exec, s[34:35]
	v_mul_f32_e32 v85, 0x3fb8aa3b, v86
	v_exp_f32_e32 v85, v85
	s_nop 0
	v_sub_f32_e32 v85, 1.0, v85
	s_andn2_saveexec_b64 s[36:37], s[36:37]
	v_fma_f32 v85, v86, 0.5, 1.0
	v_mul_f32_e64 v85, v85, -v86
	s_or_b64 exec, exec, s[36:37]
	v_add_f32_e32 v83, v83, v91
	v_mul_f32_e32 v83, 0xbfb8aa3b, v83
	v_exp_f32_e32 v83, v83
	v_max_f32_e32 v85, v85, v85
	v_max_f32_e32 v85, 0, v85
	v_sqrt_f32_e32 v85, v85
	v_add_f32_e32 v83, 1.0, v83
	v_rcp_f32_e32 v83, v83
	v_and_b32_e32 v86, 0xffff0000, v203
	v_mul_f32_e32 v83, v83, v85
	v_mul_f32_e32 v83, v83, v86
	v_cvt_pk_bf16_f32 v83, v84, v83
	v_mov_b64_e32 v[84:85], s[62:63]
	v_mad_i64_i32 v[84:85], s[34:35], v126, s87, v[84:85]
	v_lshl_add_u64 v[84:85], v[146:147], 2, v[84:85]
	global_store_dwordx4 v[84:85], v[80:83], off
.LBB0_867:
	s_or_b64 exec, exec, s[22:23]
	s_movk_i32 s6, 0x1fe0
	v_cmp_gt_i32_e64 s[52:53], s6, v196
	s_and_saveexec_b64 s[22:23], s[52:53]
	s_cbranch_execz .LBB0_885
	v_add_f32_e32 v76, v76, v96
	v_mul_f32_e32 v76, 0xbfb8aa3b, v76
	v_exp_f32_e32 v76, v76
	s_nop 0
	v_add_f32_e32 v76, 1.0, v76
	v_rcp_f32_e32 v76, v76
	s_nop 0
	v_mul_f32_e32 v76, v92, v76
	v_add_f32_e32 v81, v76, v76
	v_cmp_nlt_f32_e64 s[54:55], s95, v81
	s_and_saveexec_b64 s[34:35], s[54:55]
	s_xor_b64 s[36:37], exec, s[34:35]
	v_mul_f32_e32 v80, 0x3fb8aa3b, v81
	v_exp_f32_e32 v80, v80
	s_nop 0
	v_sub_f32_e32 v80, 1.0, v80
	s_andn2_saveexec_b64 s[36:37], s[36:37]
	v_fma_f32 v80, v81, 0.5, 1.0
	v_mul_f32_e64 v80, v80, -v81
	s_or_b64 exec, exec, s[36:37]
	v_add_f32_e32 v72, v72, v88
	v_mul_f32_e32 v72, 0xbfb8aa3b, v72
	v_exp_f32_e32 v72, v72
	v_add_f32_e32 v77, v77, v97
	v_mul_f32_e32 v77, 0xbfb8aa3b, v77
	v_exp_f32_e32 v77, v77
	v_max_f32_e32 v80, v80, v80
	v_add_f32_e32 v72, 1.0, v72
	v_max_f32_e32 v80, 0, v80
	v_rcp_f32_e32 v72, v72
	v_sqrt_f32_e32 v80, v80
	v_add_f32_e32 v77, 1.0, v77
	v_rcp_f32_e32 v77, v77
	v_lshlrev_b32_e32 v81, 16, v204
	v_mul_f32_e32 v72, v72, v80
	v_mul_f32_e32 v72, v72, v81
	v_cvt_pk_bf16_f32 v72, v76, v72
	v_mul_f32_e32 v76, v93, v77
	v_add_f32_e32 v80, v76, v76
	v_cmp_nlt_f32_e64 s[54:55], s95, v80
	s_and_saveexec_b64 s[34:35], s[54:55]
	s_xor_b64 s[36:37], exec, s[34:35]
	v_mul_f32_e32 v77, 0x3fb8aa3b, v80
	v_exp_f32_e32 v77, v77
	s_nop 0
	v_sub_f32_e32 v77, 1.0, v77
	s_andn2_saveexec_b64 s[36:37], s[36:37]
	v_fma_f32 v77, v80, 0.5, 1.0
	v_mul_f32_e64 v77, v77, -v80
	s_or_b64 exec, exec, s[36:37]
	v_add_f32_e32 v73, v73, v89
	v_mul_f32_e32 v73, 0xbfb8aa3b, v73
; __device__ __forceinline__ unsigned cvt_pk_bf16(float lo, float hi) { unsigned r; asm volatile("v_cvt_pk_bf16_f32 %0, %1, %2" : "=v"(r) : "v"(lo), "v"(hi)); return r; }
; __device__ __forceinline__ float bflo(unsigned w) { return __uint_as_float(w << 16); }
; __device__ __forceinline__ float bfhi(unsigned w) { return __uint_as_float(w & 0xffff0000u); }
; __device__ __forceinline__ float fsigmoid(float x) { return __builtin_amdgcn_rcpf(1.0f + __expf(-x)); }
;     __device__ __forceinline__ void operator()(const f32x4 (&acc)[2][2][4][2], const Unit& u, int wr, int wc, int fr, int fq) const {
;     ...
;         for (int n = 0; n < 2; ++n) { const f32x4 ba = *(const f32x4*)(bga + ch0 + 16 * n), bx = *(const f32x4*)(bgx + ch0 + 16 * n), lv = *(const f32x4*)(ll + ch0 + 16 * n);
; #pragma unroll
;             for (int ai = 0; ai < 2; ++ai) { u32x2 xq[4];
; #pragma unroll
;                 for (int m = 0; m < 4; ++m) { const int row = row0 + ai * 128 + m * 16; xq[m] = *(const u32x2*)(XC + (size_t)(row < TT ? row : TT - 1) * DRNN + ch0 + 16 * n); }
;     ...
;                 for (int m = 0; m < 4; ++m) { const int row = row0 + ai * 128 + m * 16;
;                     if (row < TT) { const size_t off = (size_t)row * DRNN + ch0 + 16 * n; const u32x2 xw = xq[m]; const f32x4 xc = (f32x4){bflo(xw.x), bfhi(xw.x), bflo(xw.y), bfhi(xw.y)}; u32x4 o;
; #pragma unroll
;                         for (int i = 0; i < 4; ++i) { const float r = fsigmoid(acc[ai][0][m][n][i] + ba[i]), ig = fsigmoid(acc[ai][1][m][n][i] + bx[i]);
;                             const float la = r * lv[i], x2 = la + la, m = x2 > -1e-3f ? -x2 * fmaf(x2, 0.5f, 1.0f) : 1.0f - __expf(x2);
;                             o[i] = cvt_pk_bf16(la, __builtin_amdgcn_sqrtf(fmaxf(m, 0.0f)) * ig * xc[i]); }
;                         *(u32x4*)(AB + off) = o; } }
	v_exp_f32_e32 v73, v73
	v_add_f32_e32 v78, v78, v98
	v_mul_f32_e32 v78, 0xbfb8aa3b, v78
	v_exp_f32_e32 v78, v78
	v_max_f32_e32 v77, v77, v77
	v_add_f32_e32 v73, 1.0, v73
	v_max_f32_e32 v77, 0, v77
	v_rcp_f32_e32 v73, v73
	v_sqrt_f32_e32 v77, v77
	v_add_f32_e32 v78, 1.0, v78
	v_rcp_f32_e32 v78, v78
	v_and_b32_e32 v80, 0xffff0000, v204
	v_mul_f32_e32 v73, v73, v77
	v_mul_f32_e32 v73, v73, v80
	v_cvt_pk_bf16_f32 v73, v76, v73
	v_mul_f32_e32 v76, v94, v78
	v_add_f32_e32 v78, v76, v76
	v_cmp_nlt_f32_e64 s[54:55], s95, v78
	s_and_saveexec_b64 s[34:35], s[54:55]
	s_xor_b64 s[36:37], exec, s[34:35]
	v_mul_f32_e32 v77, 0x3fb8aa3b, v78
	v_exp_f32_e32 v77, v77
	s_nop 0
	v_sub_f32_e32 v77, 1.0, v77
	s_andn2_saveexec_b64 s[36:37], s[36:37]
	v_fma_f32 v77, v78, 0.5, 1.0
	v_mul_f32_e64 v77, v77, -v78
	s_or_b64 exec, exec, s[36:37]
	v_add_f32_e32 v74, v74, v90
	v_mul_f32_e32 v74, 0xbfb8aa3b, v74
	v_exp_f32_e32 v74, v74
	v_add_f32_e32 v78, v79, v99
	v_mul_f32_e32 v78, 0xbfb8aa3b, v78
	v_exp_f32_e32 v78, v78
	v_max_f32_e32 v77, v77, v77
	v_add_f32_e32 v74, 1.0, v74
	v_max_f32_e32 v77, 0, v77
	v_rcp_f32_e32 v74, v74
	v_sqrt_f32_e32 v77, v77
	v_add_f32_e32 v78, 1.0, v78
	v_rcp_f32_e32 v78, v78
	v_lshlrev_b32_e32 v79, 16, v205
	v_mul_f32_e32 v74, v74, v77
	v_mul_f32_e32 v74, v74, v79
	v_cvt_pk_bf16_f32 v74, v76, v74
	v_mul_f32_e32 v76, v95, v78
	v_add_f32_e32 v78, v76, v76
	v_cmp_nlt_f32_e64 s[54:55], s95, v78
	s_and_saveexec_b64 s[34:35], s[54:55]
	s_xor_b64 s[36:37], exec, s[34:35]
	v_mul_f32_e32 v77, 0x3fb8aa3b, v78
	v_exp_f32_e32 v77, v77
	s_nop 0
	v_sub_f32_e32 v77, 1.0, v77
	s_andn2_saveexec_b64 s[36:37], s[36:37]
	v_fma_f32 v77, v78, 0.5, 1.0
	v_mul_f32_e64 v77, v77, -v78
	s_or_b64 exec, exec, s[36:37]
	v_add_f32_e32 v75, v75, v91
	v_mul_f32_e32 v75, 0xbfb8aa3b, v75
	v_exp_f32_e32 v75, v75
	v_max_f32_e32 v77, v77, v77
	v_max_f32_e32 v77, 0, v77
	v_sqrt_f32_e32 v77, v77
	v_add_f32_e32 v75, 1.0, v75
	v_rcp_f32_e32 v75, v75
	v_and_b32_e32 v78, 0xffff0000, v205
	v_mul_f32_e32 v75, v75, v77
	v_mul_f32_e32 v75, v75, v78
	v_cvt_pk_bf16_f32 v75, v76, v75
	v_mov_b64_e32 v[76:77], s[62:63]
	v_mad_i64_i32 v[76:77], s[34:35], v125, s87, v[76:77]
	v_lshl_add_u64 v[76:77], v[146:147], 2, v[76:77]
	global_store_dwordx4 v[76:77], v[72:75], off
.LBB0_885:
	s_or_b64 exec, exec, s[22:23]
	s_movk_i32 s6, 0x1fd0
	v_cmp_gt_i32_e64 s[54:55], s6, v196
	s_and_saveexec_b64 s[22:23], s[54:55]
	s_cbranch_execz .LBB0_903
	v_add_f32_e32 v68, v68, v96
	v_mul_f32_e32 v68, 0xbfb8aa3b, v68
	v_exp_f32_e32 v68, v68
	s_nop 0
	v_add_f32_e32 v68, 1.0, v68
	v_rcp_f32_e32 v68, v68
	s_nop 0
	v_mul_f32_e32 v68, v92, v68
	v_add_f32_e32 v73, v68, v68
	v_cmp_nlt_f32_e64 s[56:57], s95, v73
	s_and_saveexec_b64 s[34:35], s[56:57]
	s_xor_b64 s[36:37], exec, s[34:35]
	v_mul_f32_e32 v72, 0x3fb8aa3b, v73
	v_exp_f32_e32 v72, v72
	s_nop 0
	v_sub_f32_e32 v72, 1.0, v72
	s_andn2_saveexec_b64 s[36:37], s[36:37]
	v_fma_f32 v72, v73, 0.5, 1.0
	v_mul_f32_e64 v72, v72, -v73
	s_or_b64 exec, exec, s[36:37]
	v_add_f32_e32 v64, v64, v88
	v_mul_f32_e32 v64, 0xbfb8aa3b, v64
	v_exp_f32_e32 v64, v64
	v_add_f32_e32 v69, v69, v97
	v_mul_f32_e32 v69, 0xbfb8aa3b, v69
	v_exp_f32_e32 v69, v69
	v_max_f32_e32 v72, v72, v72
	v_add_f32_e32 v64, 1.0, v64
	v_max_f32_e32 v72, 0, v72
	v_rcp_f32_e32 v64, v64
	v_sqrt_f32_e32 v72, v72
	v_add_f32_e32 v69, 1.0, v69
	v_rcp_f32_e32 v69, v69
	v_lshlrev_b32_e32 v73, 16, v206
	v_mul_f32_e32 v64, v64, v72
	v_mul_f32_e32 v64, v64, v73
	v_cvt_pk_bf16_f32 v64, v68, v64
	v_mul_f32_e32 v68, v93, v69
	v_add_f32_e32 v72, v68, v68
	v_cmp_nlt_f32_e64 s[56:57], s95, v72
	s_and_saveexec_b64 s[34:35], s[56:57]
	s_xor_b64 s[36:37], exec, s[34:35]
	v_mul_f32_e32 v69, 0x3fb8aa3b, v72
	v_exp_f32_e32 v69, v69
	s_nop 0
	v_sub_f32_e32 v69, 1.0, v69
	s_andn2_saveexec_b64 s[36:37], s[36:37]
	v_fma_f32 v69, v72, 0.5, 1.0
	v_mul_f32_e64 v69, v69, -v72
	s_or_b64 exec, exec, s[36:37]
	v_add_f32_e32 v65, v65, v89
	v_mul_f32_e32 v65, 0xbfb8aa3b, v65
	v_exp_f32_e32 v65, v65
	v_add_f32_e32 v70, v70, v98
	v_mul_f32_e32 v70, 0xbfb8aa3b, v70
	v_exp_f32_e32 v70, v70
	v_max_f32_e32 v69, v69, v69
	v_add_f32_e32 v65, 1.0, v65
	v_max_f32_e32 v69, 0, v69
	v_rcp_f32_e32 v65, v65
	v_sqrt_f32_e32 v69, v69
	v_add_f32_e32 v70, 1.0, v70
	v_rcp_f32_e32 v70, v70
	v_and_b32_e32 v72, 0xffff0000, v206
	v_mul_f32_e32 v65, v65, v69
	v_mul_f32_e32 v65, v65, v72
	v_cvt_pk_bf16_f32 v65, v68, v65
	v_mul_f32_e32 v68, v94, v70
	v_add_f32_e32 v70, v68, v68
	v_cmp_nlt_f32_e64 s[56:57], s95, v70
	s_and_saveexec_b64 s[34:35], s[56:57]
	s_xor_b64 s[36:37], exec, s[34:35]
	v_mul_f32_e32 v69, 0x3fb8aa3b, v70
	v_exp_f32_e32 v69, v69
	s_nop 0
	v_sub_f32_e32 v69, 1.0, v69
	s_andn2_saveexec_b64 s[36:37], s[36:37]
	v_fma_f32 v69, v70, 0.5, 1.0
	v_mul_f32_e64 v69, v69, -v70
	s_or_b64 exec, exec, s[36:37]
	v_add_f32_e32 v66, v66, v90
	v_mul_f32_e32 v66, 0xbfb8aa3b, v66
	v_exp_f32_e32 v66, v66
	v_add_f32_e32 v70, v71, v99
	v_mul_f32_e32 v70, 0xbfb8aa3b, v70
	v_exp_f32_e32 v70, v70
	v_max_f32_e32 v69, v69, v69
	v_add_f32_e32 v66, 1.0, v66
	v_max_f32_e32 v69, 0, v69
	v_rcp_f32_e32 v66, v66
	v_sqrt_f32_e32 v69, v69
	v_add_f32_e32 v70, 1.0, v70
	v_rcp_f32_e32 v70, v70
	v_lshlrev_b32_e32 v71, 16, v207
	v_mul_f32_e32 v66, v66, v69
	v_mul_f32_e32 v66, v66, v71
	v_cvt_pk_bf16_f32 v66, v68, v66
	v_mul_f32_e32 v68, v95, v70
	v_add_f32_e32 v70, v68, v68
	v_cmp_nlt_f32_e64 s[56:57], s95, v70
	s_and_saveexec_b64 s[34:35], s[56:57]
	s_xor_b64 s[36:37], exec, s[34:35]
	v_mul_f32_e32 v69, 0x3fb8aa3b, v70
	v_exp_f32_e32 v69, v69
	s_nop 0
	v_sub_f32_e32 v69, 1.0, v69
	s_andn2_saveexec_b64 s[36:37], s[36:37]
	v_fma_f32 v69, v70, 0.5, 1.0
	v_mul_f32_e64 v69, v69, -v70
	s_or_b64 exec, exec, s[36:37]
	v_add_f32_e32 v67, v67, v91
	v_mul_f32_e32 v67, 0xbfb8aa3b, v67
	v_exp_f32_e32 v67, v67
	v_max_f32_e32 v69, v69, v69
	v_max_f32_e32 v69, 0, v69
	v_sqrt_f32_e32 v69, v69
	v_add_f32_e32 v67, 1.0, v67
	v_rcp_f32_e32 v67, v67
	v_and_b32_e32 v70, 0xffff0000, v207
	v_mul_f32_e32 v67, v67, v69
	v_mul_f32_e32 v67, v67, v70
	v_cvt_pk_bf16_f32 v67, v68, v67
	v_mov_b64_e32 v[68:69], s[62:63]
	v_mad_i64_i32 v[68:69], s[34:35], v124, s87, v[68:69]
	v_lshl_add_u64 v[68:69], v[146:147], 2, v[68:69]
	global_store_dwordx4 v[68:69], v[64:67], off
.LBB0_903:
	s_or_b64 exec, exec, s[22:23]
	s_and_saveexec_b64 s[22:23], vcc
	s_cbranch_execnz .LBB0_906
	s_or_b64 exec, exec, s[22:23]
	s_and_saveexec_b64 s[22:23], s[42:43]
	s_cbranch_execnz .LBB0_923

; __device__ __forceinline__ unsigned cvt_pk_bf16(float lo, float hi) { unsigned r; asm volatile("v_cvt_pk_bf16_f32 %0, %1, %2" : "=v"(r) : "v"(lo), "v"(hi)); return r; }
; __device__ __forceinline__ float bflo(unsigned w) { return __uint_as_float(w << 16); }
; __device__ __forceinline__ float bfhi(unsigned w) { return __uint_as_float(w & 0xffff0000u); }
; __device__ __forceinline__ float fsigmoid(float x) { return __builtin_amdgcn_rcpf(1.0f + __expf(-x)); }
;     __device__ __forceinline__ void operator()(const f32x4 (&acc)[2][2][4][2], const Unit& u, int wr, int wc, int fr, int fq) const {
;     ...
;                 for (int m = 0; m < 4; ++m) { const int row = row0 + ai * 128 + m * 16;
;                     if (row < TT) { const size_t off = (size_t)row * DRNN + ch0 + 16 * n; const u32x2 xw = xq[m]; const f32x4 xc = (f32x4){bflo(xw.x), bfhi(xw.x), bflo(xw.y), bfhi(xw.y)}; u32x4 o;
; #pragma unroll
;                         for (int i = 0; i < 4; ++i) { const float r = fsigmoid(acc[ai][0][m][n][i] + ba[i]), ig = fsigmoid(acc[ai][1][m][n][i] + bx[i]);
;                             const float la = r * lv[i], x2 = la + la, m = x2 > -1e-3f ? -x2 * fmaf(x2, 0.5f, 1.0f) : 1.0f - __expf(x2);
;                             o[i] = cvt_pk_bf16(la, __builtin_amdgcn_sqrtf(fmaxf(m, 0.0f)) * ig * xc[i]); }
;                         *(u32x4*)(AB + off) = o; } }
.LBB0_906:
	v_add_f32_e32 v60, v60, v226
	v_mul_f32_e32 v60, 0xbfb8aa3b, v60
	v_exp_f32_e32 v60, v60
	s_nop 0
	v_add_f32_e32 v60, 1.0, v60
	v_rcp_f32_e32 v60, v60
	s_nop 0
	v_mul_f32_e32 v60, v234, v60
	v_add_f32_e32 v85, v60, v60
	v_cmp_nlt_f32_e32 vcc, s95, v85
	s_and_saveexec_b64 s[34:35], vcc
	s_xor_b64 s[36:37], exec, s[34:35]
	v_mul_f32_e32 v84, 0x3fb8aa3b, v85
	v_exp_f32_e32 v84, v84
	s_nop 0
	v_sub_f32_e32 v84, 1.0, v84
	s_andn2_saveexec_b64 s[36:37], s[36:37]
	v_fma_f32 v84, v85, 0.5, 1.0
	v_mul_f32_e64 v84, v84, -v85
	s_or_b64 exec, exec, s[36:37]
	v_add_f32_e32 v56, v56, v230
	v_mul_f32_e32 v56, 0xbfb8aa3b, v56
	v_exp_f32_e32 v56, v56
	v_add_f32_e32 v61, v61, v227
	v_mul_f32_e32 v61, 0xbfb8aa3b, v61
	v_exp_f32_e32 v61, v61
	v_max_f32_e32 v84, v84, v84
	v_add_f32_e32 v56, 1.0, v56
	v_max_f32_e32 v84, 0, v84
	v_rcp_f32_e32 v56, v56
	v_sqrt_f32_e32 v84, v84
	v_add_f32_e32 v61, 1.0, v61
	v_rcp_f32_e32 v61, v61
	v_lshlrev_b32_e32 v85, 16, v244
	v_mul_f32_e32 v56, v56, v84
	v_mul_f32_e32 v56, v56, v85
	v_cvt_pk_bf16_f32 v56, v60, v56
	v_mul_f32_e32 v60, v235, v61
	v_add_f32_e32 v84, v60, v60
	v_cmp_nlt_f32_e32 vcc, s95, v84
	s_and_saveexec_b64 s[34:35], vcc
	s_xor_b64 s[36:37], exec, s[34:35]
	v_mul_f32_e32 v61, 0x3fb8aa3b, v84
	v_exp_f32_e32 v61, v61
	s_nop 0
	v_sub_f32_e32 v61, 1.0, v61
	s_andn2_saveexec_b64 s[36:37], s[36:37]
	v_fma_f32 v61, v84, 0.5, 1.0
	v_mul_f32_e64 v61, v61, -v84
	s_or_b64 exec, exec, s[36:37]
	v_add_f32_e32 v57, v57, v231
	v_mul_f32_e32 v57, 0xbfb8aa3b, v57
	v_exp_f32_e32 v57, v57
	v_add_f32_e32 v62, v62, v228
	v_mul_f32_e32 v62, 0xbfb8aa3b, v62
	v_exp_f32_e32 v62, v62
	v_max_f32_e32 v61, v61, v61
	v_add_f32_e32 v57, 1.0, v57
	v_max_f32_e32 v61, 0, v61
	v_rcp_f32_e32 v57, v57
	v_sqrt_f32_e32 v61, v61
	v_add_f32_e32 v62, 1.0, v62
	v_rcp_f32_e32 v62, v62
	v_and_b32_e32 v244, 0xffff0000, v244
	v_mul_f32_e32 v57, v57, v61
	v_mul_f32_e32 v57, v57, v244
	v_cvt_pk_bf16_f32 v57, v60, v57
	v_mul_f32_e32 v60, v236, v62
	v_add_f32_e32 v62, v60, v60
	v_cmp_nlt_f32_e32 vcc, s95, v62
	s_and_saveexec_b64 s[34:35], vcc
	s_xor_b64 s[36:37], exec, s[34:35]
	v_mul_f32_e32 v61, 0x3fb8aa3b, v62
	v_exp_f32_e32 v61, v61
	s_nop 0
	v_sub_f32_e32 v61, 1.0, v61
	s_andn2_saveexec_b64 s[36:37], s[36:37]
	v_fma_f32 v61, v62, 0.5, 1.0
	v_mul_f32_e64 v61, v61, -v62
	s_or_b64 exec, exec, s[36:37]
	v_add_f32_e32 v58, v58, v232
	v_mul_f32_e32 v58, 0xbfb8aa3b, v58
	v_exp_f32_e32 v58, v58
	v_add_f32_e32 v62, v63, v229
	v_mul_f32_e32 v62, 0xbfb8aa3b, v62
	v_exp_f32_e32 v62, v62
	v_max_f32_e32 v61, v61, v61
	v_add_f32_e32 v58, 1.0, v58
	v_max_f32_e32 v61, 0, v61
	v_rcp_f32_e32 v58, v58
	v_sqrt_f32_e32 v61, v61
	v_add_f32_e32 v62, 1.0, v62
	v_rcp_f32_e32 v62, v62
	v_lshlrev_b32_e32 v63, 16, v245
	v_mul_f32_e32 v58, v58, v61
	v_mul_f32_e32 v58, v58, v63
	v_cvt_pk_bf16_f32 v58, v60, v58
	v_mul_f32_e32 v60, v237, v62
	v_add_f32_e32 v62, v60, v60
	v_cmp_nlt_f32_e32 vcc, s95, v62
	s_and_saveexec_b64 s[34:35], vcc
	s_xor_b64 s[36:37], exec, s[34:35]
	v_mul_f32_e32 v61, 0x3fb8aa3b, v62
	v_exp_f32_e32 v61, v61
	s_nop 0
	v_sub_f32_e32 v61, 1.0, v61
	s_andn2_saveexec_b64 s[36:37], s[36:37]
	v_fma_f32 v61, v62, 0.5, 1.0
	v_mul_f32_e64 v61, v61, -v62
	s_or_b64 exec, exec, s[36:37]
	v_add_f32_e32 v59, v59, v233
	v_mul_f32_e32 v59, 0xbfb8aa3b, v59
	v_exp_f32_e32 v59, v59
	v_max_f32_e32 v61, v61, v61
	v_max_f32_e32 v61, 0, v61
	v_sqrt_f32_e32 v61, v61
	v_add_f32_e32 v59, 1.0, v59
	v_rcp_f32_e32 v59, v59
	v_and_b32_e32 v62, 0xffff0000, v245
	v_mul_f32_e32 v59, v59, v61
	v_mul_f32_e32 v59, v59, v62
	v_cvt_pk_bf16_f32 v59, v60, v59
	v_mov_b64_e32 v[60:61], s[62:63]
	v_mad_i64_i32 v[60:61], s[34:35], v196, s87, v[60:61]
	v_lshl_add_u64 v[60:61], v[146:147], 2, v[60:61]
	global_store_dwordx4 v[60:61], v[56:59], off offset:64
	s_or_b64 exec, exec, s[22:23]
	s_and_saveexec_b64 s[22:23], s[42:43]
	s_cbranch_execz .LBB0_905
.LBB0_923:
	v_add_f32_e32 v52, v52, v226
	v_mul_f32_e32 v52, 0xbfb8aa3b, v52
	v_exp_f32_e32 v52, v52
	s_nop 0
	v_add_f32_e32 v52, 1.0, v52
	v_rcp_f32_e32 v52, v52
	s_nop 0
	v_mul_f32_e32 v52, v234, v52
	v_add_f32_e32 v57, v52, v52
	v_cmp_nlt_f32_e32 vcc, s95, v57
	s_and_saveexec_b64 s[34:35], vcc
	s_xor_b64 s[36:37], exec, s[34:35]
	v_mul_f32_e32 v56, 0x3fb8aa3b, v57
	v_exp_f32_e32 v56, v56
	s_nop 0
	v_sub_f32_e32 v56, 1.0, v56
	s_andn2_saveexec_b64 s[36:37], s[36:37]
	v_fma_f32 v56, v57, 0.5, 1.0
	v_mul_f32_e64 v56, v56, -v57
	s_or_b64 exec, exec, s[36:37]
	v_add_f32_e32 v48, v48, v230
	v_mul_f32_e32 v48, 0xbfb8aa3b, v48
	v_exp_f32_e32 v48, v48
	v_add_f32_e32 v53, v53, v227
	v_mul_f32_e32 v53, 0xbfb8aa3b, v53
	v_exp_f32_e32 v53, v53
	v_max_f32_e32 v56, v56, v56
	v_add_f32_e32 v48, 1.0, v48
	v_max_f32_e32 v56, 0, v56
	v_rcp_f32_e32 v48, v48
	v_sqrt_f32_e32 v56, v56
	v_add_f32_e32 v53, 1.0, v53
	v_rcp_f32_e32 v53, v53
	v_lshlrev_b32_e32 v57, 16, v238
	v_mul_f32_e32 v48, v48, v56
	v_mul_f32_e32 v48, v48, v57
	v_cvt_pk_bf16_f32 v48, v52, v48
	v_mul_f32_e32 v52, v235, v53
	v_add_f32_e32 v56, v52, v52
	v_cmp_nlt_f32_e32 vcc, s95, v56
	s_and_saveexec_b64 s[34:35], vcc
	s_xor_b64 s[36:37], exec, s[34:35]
	v_mul_f32_e32 v53, 0x3fb8aa3b, v56
	v_exp_f32_e32 v53, v53
	s_nop 0
	v_sub_f32_e32 v53, 1.0, v53
	s_andn2_saveexec_b64 s[36:37], s[36:37]
	v_fma_f32 v53, v56, 0.5, 1.0
	v_mul_f32_e64 v53, v53, -v56
	s_or_b64 exec, exec, s[36:37]
	v_add_f32_e32 v49, v49, v231
	v_mul_f32_e32 v49, 0xbfb8aa3b, v49
	v_exp_f32_e32 v49, v49
	v_add_f32_e32 v54, v54, v228
	v_mul_f32_e32 v54, 0xbfb8aa3b, v54
	v_exp_f32_e32 v54, v54
	v_max_f32_e32 v53, v53, v53
	v_add_f32_e32 v49, 1.0, v49
	v_max_f32_e32 v53, 0, v53
	v_rcp_f32_e32 v49, v49
	v_sqrt_f32_e32 v53, v53
	v_add_f32_e32 v54, 1.0, v54
; __device__ __forceinline__ unsigned cvt_pk_bf16(float lo, float hi) { unsigned r; asm volatile("v_cvt_pk_bf16_f32 %0, %1, %2" : "=v"(r) : "v"(lo), "v"(hi)); return r; }
; __device__ __forceinline__ float bflo(unsigned w) { return __uint_as_float(w << 16); }
; __device__ __forceinline__ float bfhi(unsigned w) { return __uint_as_float(w & 0xffff0000u); }
; __device__ __forceinline__ float fsigmoid(float x) { return __builtin_amdgcn_rcpf(1.0f + __expf(-x)); }
;     __device__ __forceinline__ void operator()(const f32x4 (&acc)[2][2][4][2], const Unit& u, int wr, int wc, int fr, int fq) const {
;     ...
;                 for (int m = 0; m < 4; ++m) { const int row = row0 + ai * 128 + m * 16;
;                     if (row < TT) { const size_t off = (size_t)row * DRNN + ch0 + 16 * n; const u32x2 xw = xq[m]; const f32x4 xc = (f32x4){bflo(xw.x), bfhi(xw.x), bflo(xw.y), bfhi(xw.y)}; u32x4 o;
; #pragma unroll
;                         for (int i = 0; i < 4; ++i) { const float r = fsigmoid(acc[ai][0][m][n][i] + ba[i]), ig = fsigmoid(acc[ai][1][m][n][i] + bx[i]);
;                             const float la = r * lv[i], x2 = la + la, m = x2 > -1e-3f ? -x2 * fmaf(x2, 0.5f, 1.0f) : 1.0f - __expf(x2);
;                             o[i] = cvt_pk_bf16(la, __builtin_amdgcn_sqrtf(fmaxf(m, 0.0f)) * ig * xc[i]); }
;                         *(u32x4*)(AB + off) = o; } }
	v_rcp_f32_e32 v54, v54
	v_and_b32_e32 v56, 0xffff0000, v238
	v_mul_f32_e32 v49, v49, v53
	v_mul_f32_e32 v49, v49, v56
	v_cvt_pk_bf16_f32 v49, v52, v49
	v_mul_f32_e32 v52, v236, v54
	v_add_f32_e32 v54, v52, v52
	v_cmp_nlt_f32_e32 vcc, s95, v54
	s_and_saveexec_b64 s[34:35], vcc
	s_xor_b64 s[36:37], exec, s[34:35]
	v_mul_f32_e32 v53, 0x3fb8aa3b, v54
	v_exp_f32_e32 v53, v53
	s_nop 0
	v_sub_f32_e32 v53, 1.0, v53
	s_andn2_saveexec_b64 s[36:37], s[36:37]
	v_fma_f32 v53, v54, 0.5, 1.0
	v_mul_f32_e64 v53, v53, -v54
	s_or_b64 exec, exec, s[36:37]
	v_add_f32_e32 v50, v50, v232
	v_mul_f32_e32 v50, 0xbfb8aa3b, v50
	v_exp_f32_e32 v50, v50
	v_add_f32_e32 v54, v55, v229
	v_mul_f32_e32 v54, 0xbfb8aa3b, v54
	v_exp_f32_e32 v54, v54
	v_max_f32_e32 v53, v53, v53
	v_add_f32_e32 v50, 1.0, v50
	v_max_f32_e32 v53, 0, v53
	v_rcp_f32_e32 v50, v50
	v_sqrt_f32_e32 v53, v53
	v_add_f32_e32 v54, 1.0, v54
	v_rcp_f32_e32 v54, v54
	v_lshlrev_b32_e32 v55, 16, v239
	v_mul_f32_e32 v50, v50, v53
	v_mul_f32_e32 v50, v50, v55
	v_cvt_pk_bf16_f32 v50, v52, v50
	v_mul_f32_e32 v52, v237, v54
	v_add_f32_e32 v54, v52, v52
	v_cmp_nlt_f32_e32 vcc, s95, v54
	s_and_saveexec_b64 s[34:35], vcc
	s_xor_b64 s[36:37], exec, s[34:35]
	v_mul_f32_e32 v53, 0x3fb8aa3b, v54
	v_exp_f32_e32 v53, v53
	s_nop 0
	v_sub_f32_e32 v53, 1.0, v53
	s_andn2_saveexec_b64 s[36:37], s[36:37]
	v_fma_f32 v53, v54, 0.5, 1.0
	v_mul_f32_e64 v53, v53, -v54
	s_or_b64 exec, exec, s[36:37]
	v_add_f32_e32 v51, v51, v233
	v_mul_f32_e32 v51, 0xbfb8aa3b, v51
	v_exp_f32_e32 v51, v51
	v_max_f32_e32 v53, v53, v53
	v_max_f32_e32 v53, 0, v53
	v_sqrt_f32_e32 v53, v53
	v_add_f32_e32 v51, 1.0, v51
	v_rcp_f32_e32 v51, v51
	v_and_b32_e32 v54, 0xffff0000, v239
	v_mul_f32_e32 v51, v51, v53
	v_mul_f32_e32 v51, v51, v54
	v_cvt_pk_bf16_f32 v51, v52, v51
	v_mov_b64_e32 v[52:53], s[62:63]
	v_mad_i64_i32 v[52:53], s[34:35], v195, s87, v[52:53]
	v_lshl_add_u64 v[52:53], v[146:147], 2, v[52:53]
	global_store_dwordx4 v[52:53], v[48:51], off offset:64
	s_or_b64 exec, exec, s[22:23]
	s_and_saveexec_b64 s[22:23], s[44:45]
	s_cbranch_execz .LBB0_957
.LBB0_940:
	v_add_f32_e32 v44, v44, v226
	v_mul_f32_e32 v44, 0xbfb8aa3b, v44
	v_exp_f32_e32 v44, v44
	s_nop 0
	v_add_f32_e32 v44, 1.0, v44
	v_rcp_f32_e32 v44, v44
	s_nop 0
	v_mul_f32_e32 v44, v234, v44
	v_add_f32_e32 v49, v44, v44
	v_cmp_nlt_f32_e32 vcc, s95, v49
	s_and_saveexec_b64 s[34:35], vcc
	s_xor_b64 s[36:37], exec, s[34:35]
	v_mul_f32_e32 v48, 0x3fb8aa3b, v49
	v_exp_f32_e32 v48, v48
	s_nop 0
	v_sub_f32_e32 v48, 1.0, v48
	s_andn2_saveexec_b64 s[36:37], s[36:37]
	v_fma_f32 v48, v49, 0.5, 1.0
	v_mul_f32_e64 v48, v48, -v49
	s_or_b64 exec, exec, s[36:37]
	v_add_f32_e32 v40, v40, v230
	v_mul_f32_e32 v40, 0xbfb8aa3b, v40
	v_exp_f32_e32 v40, v40
	v_add_f32_e32 v45, v45, v227
	v_mul_f32_e32 v45, 0xbfb8aa3b, v45
	v_exp_f32_e32 v45, v45
	v_max_f32_e32 v48, v48, v48
	v_add_f32_e32 v40, 1.0, v40
	v_max_f32_e32 v48, 0, v48
	v_rcp_f32_e32 v40, v40
	v_sqrt_f32_e32 v48, v48
	v_add_f32_e32 v45, 1.0, v45
	v_rcp_f32_e32 v45, v45
	v_lshlrev_b32_e32 v49, 16, v240
	v_mul_f32_e32 v40, v40, v48
	v_mul_f32_e32 v40, v40, v49
	v_cvt_pk_bf16_f32 v40, v44, v40
	v_mul_f32_e32 v44, v235, v45
	v_add_f32_e32 v48, v44, v44
	v_cmp_nlt_f32_e32 vcc, s95, v48
	s_and_saveexec_b64 s[34:35], vcc
	s_xor_b64 s[36:37], exec, s[34:35]
	v_mul_f32_e32 v45, 0x3fb8aa3b, v48
	v_exp_f32_e32 v45, v45
	s_nop 0
	v_sub_f32_e32 v45, 1.0, v45
	s_andn2_saveexec_b64 s[36:37], s[36:37]
	v_fma_f32 v45, v48, 0.5, 1.0
	v_mul_f32_e64 v45, v45, -v48
	s_or_b64 exec, exec, s[36:37]
	v_add_f32_e32 v41, v41, v231
	v_mul_f32_e32 v41, 0xbfb8aa3b, v41
	v_exp_f32_e32 v41, v41
	v_add_f32_e32 v46, v46, v228
	v_mul_f32_e32 v46, 0xbfb8aa3b, v46
	v_exp_f32_e32 v46, v46
	v_max_f32_e32 v45, v45, v45
	v_add_f32_e32 v41, 1.0, v41
	v_max_f32_e32 v45, 0, v45
	v_rcp_f32_e32 v41, v41
	v_sqrt_f32_e32 v45, v45
	v_add_f32_e32 v46, 1.0, v46
	v_rcp_f32_e32 v46, v46
	v_and_b32_e32 v48, 0xffff0000, v240
	v_mul_f32_e32 v41, v41, v45
	v_mul_f32_e32 v41, v41, v48
	v_cvt_pk_bf16_f32 v41, v44, v41
	v_mul_f32_e32 v44, v236, v46
	v_add_f32_e32 v46, v44, v44
	v_cmp_nlt_f32_e32 vcc, s95, v46
	s_and_saveexec_b64 s[34:35], vcc
	s_xor_b64 s[36:37], exec, s[34:35]
	v_mul_f32_e32 v45, 0x3fb8aa3b, v46
	v_exp_f32_e32 v45, v45
	s_nop 0
	v_sub_f32_e32 v45, 1.0, v45
	s_andn2_saveexec_b64 s[36:37], s[36:37]
	v_fma_f32 v45, v46, 0.5, 1.0
	v_mul_f32_e64 v45, v45, -v46
	s_or_b64 exec, exec, s[36:37]
	v_add_f32_e32 v42, v42, v232
	v_mul_f32_e32 v42, 0xbfb8aa3b, v42
	v_exp_f32_e32 v42, v42
	v_add_f32_e32 v46, v47, v229
	v_mul_f32_e32 v46, 0xbfb8aa3b, v46
	v_exp_f32_e32 v46, v46
	v_max_f32_e32 v45, v45, v45
	v_add_f32_e32 v42, 1.0, v42
	v_max_f32_e32 v45, 0, v45
	v_rcp_f32_e32 v42, v42
	v_sqrt_f32_e32 v45, v45
	v_add_f32_e32 v46, 1.0, v46
	v_rcp_f32_e32 v46, v46
	v_lshlrev_b32_e32 v47, 16, v241
	v_mul_f32_e32 v42, v42, v45
	v_mul_f32_e32 v42, v42, v47
	v_cvt_pk_bf16_f32 v42, v44, v42
	v_mul_f32_e32 v44, v237, v46
	v_add_f32_e32 v46, v44, v44
	v_cmp_nlt_f32_e32 vcc, s95, v46
	s_and_saveexec_b64 s[34:35], vcc
	s_xor_b64 s[36:37], exec, s[34:35]
	v_mul_f32_e32 v45, 0x3fb8aa3b, v46
	v_exp_f32_e32 v45, v45
	s_nop 0
	v_sub_f32_e32 v45, 1.0, v45
	s_andn2_saveexec_b64 s[36:37], s[36:37]
	v_fma_f32 v45, v46, 0.5, 1.0
	v_mul_f32_e64 v45, v45, -v46
	s_or_b64 exec, exec, s[36:37]
	v_add_f32_e32 v43, v43, v233
	v_mul_f32_e32 v43, 0xbfb8aa3b, v43
	v_exp_f32_e32 v43, v43
	v_max_f32_e32 v45, v45, v45
	v_max_f32_e32 v45, 0, v45
	v_sqrt_f32_e32 v45, v45
	v_add_f32_e32 v43, 1.0, v43
	v_rcp_f32_e32 v43, v43
	v_and_b32_e32 v46, 0xffff0000, v241
	v_mul_f32_e32 v43, v43, v45
	v_mul_f32_e32 v43, v43, v46
	v_cvt_pk_bf16_f32 v43, v44, v43
	v_mov_b64_e32 v[44:45], s[62:63]
	v_mad_i64_i32 v[44:45], s[34:35], v194, s87, v[44:45]
	v_lshl_add_u64 v[44:45], v[146:147], 2, v[44:45]
	global_store_dwordx4 v[44:45], v[40:43], off offset:64
; __device__ __forceinline__ unsigned cvt_pk_bf16(float lo, float hi) { unsigned r; asm volatile("v_cvt_pk_bf16_f32 %0, %1, %2" : "=v"(r) : "v"(lo), "v"(hi)); return r; }
; __device__ __forceinline__ float bflo(unsigned w) { return __uint_as_float(w << 16); }
; __device__ __forceinline__ float bfhi(unsigned w) { return __uint_as_float(w & 0xffff0000u); }
; __device__ __forceinline__ float fsigmoid(float x) { return __builtin_amdgcn_rcpf(1.0f + __expf(-x)); }
;     __device__ __forceinline__ void operator()(const f32x4 (&acc)[2][2][4][2], const Unit& u, int wr, int wc, int fr, int fq) const {
;     ...
;             for (int ai = 0; ai < 2; ++ai) { u32x2 xq[4];
; #pragma unroll
;                 for (int m = 0; m < 4; ++m) { const int row = row0 + ai * 128 + m * 16; xq[m] = *(const u32x2*)(XC + (size_t)(row < TT ? row : TT - 1) * DRNN + ch0 + 16 * n); }
;     ...
;                 for (int m = 0; m < 4; ++m) { const int row = row0 + ai * 128 + m * 16;
;                     if (row < TT) { const size_t off = (size_t)row * DRNN + ch0 + 16 * n; const u32x2 xw = xq[m]; const f32x4 xc = (f32x4){bflo(xw.x), bfhi(xw.x), bflo(xw.y), bfhi(xw.y)}; u32x4 o;
; #pragma unroll
;                         for (int i = 0; i < 4; ++i) { const float r = fsigmoid(acc[ai][0][m][n][i] + ba[i]), ig = fsigmoid(acc[ai][1][m][n][i] + bx[i]);
;                             const float la = r * lv[i], x2 = la + la, m = x2 > -1e-3f ? -x2 * fmaf(x2, 0.5f, 1.0f) : 1.0f - __expf(x2);
;                             o[i] = cvt_pk_bf16(la, __builtin_amdgcn_sqrtf(fmaxf(m, 0.0f)) * ig * xc[i]); }
;                         *(u32x4*)(AB + off) = o; } }
.LBB0_957:
	s_or_b64 exec, exec, s[22:23]
	s_and_saveexec_b64 s[22:23], s[46:47]
	s_mov_b32 s33, 0xa000
	s_mov_b32 s46, 0x11000
	s_cbranch_execz .LBB0_975
	v_add_f32_e32 v36, v36, v226
	v_mul_f32_e32 v36, 0xbfb8aa3b, v36
	v_exp_f32_e32 v36, v36
	s_nop 0
	v_add_f32_e32 v36, 1.0, v36
	v_rcp_f32_e32 v36, v36
	s_nop 0
	v_mul_f32_e32 v36, v234, v36
	v_add_f32_e32 v41, v36, v36
	v_cmp_nlt_f32_e32 vcc, s95, v41
	s_and_saveexec_b64 s[34:35], vcc
	s_xor_b64 s[36:37], exec, s[34:35]
	v_mul_f32_e32 v40, 0x3fb8aa3b, v41
	v_exp_f32_e32 v40, v40
	s_nop 0
	v_sub_f32_e32 v40, 1.0, v40
	s_andn2_saveexec_b64 s[36:37], s[36:37]
	v_fma_f32 v40, v41, 0.5, 1.0
	v_mul_f32_e64 v40, v40, -v41
	s_or_b64 exec, exec, s[36:37]
	v_add_f32_e32 v32, v32, v230
	v_mul_f32_e32 v32, 0xbfb8aa3b, v32
	v_exp_f32_e32 v32, v32
	v_add_f32_e32 v37, v37, v227
	v_mul_f32_e32 v37, 0xbfb8aa3b, v37
	v_exp_f32_e32 v37, v37
	v_max_f32_e32 v40, v40, v40
	v_add_f32_e32 v32, 1.0, v32
	v_max_f32_e32 v40, 0, v40
	v_rcp_f32_e32 v32, v32
	v_sqrt_f32_e32 v40, v40
	v_add_f32_e32 v37, 1.0, v37
	v_rcp_f32_e32 v37, v37
	v_lshlrev_b32_e32 v41, 16, v242
	v_mul_f32_e32 v32, v32, v40
	v_mul_f32_e32 v32, v32, v41
	v_cvt_pk_bf16_f32 v32, v36, v32
	v_mul_f32_e32 v36, v235, v37
	v_add_f32_e32 v40, v36, v36
	v_cmp_nlt_f32_e32 vcc, s95, v40
	s_and_saveexec_b64 s[34:35], vcc
	s_xor_b64 s[36:37], exec, s[34:35]
	v_mul_f32_e32 v37, 0x3fb8aa3b, v40
	v_exp_f32_e32 v37, v37
	s_nop 0
	v_sub_f32_e32 v37, 1.0, v37
	s_andn2_saveexec_b64 s[36:37], s[36:37]
	v_fma_f32 v37, v40, 0.5, 1.0
	v_mul_f32_e64 v37, v37, -v40
	s_or_b64 exec, exec, s[36:37]
	v_add_f32_e32 v33, v33, v231
	v_mul_f32_e32 v33, 0xbfb8aa3b, v33
	v_exp_f32_e32 v33, v33
	v_add_f32_e32 v38, v38, v228
	v_mul_f32_e32 v38, 0xbfb8aa3b, v38
	v_exp_f32_e32 v38, v38
	v_max_f32_e32 v37, v37, v37
	v_add_f32_e32 v33, 1.0, v33
	v_max_f32_e32 v37, 0, v37
	v_rcp_f32_e32 v33, v33
	v_sqrt_f32_e32 v37, v37
	v_add_f32_e32 v38, 1.0, v38
	v_rcp_f32_e32 v38, v38
	v_and_b32_e32 v40, 0xffff0000, v242
	v_mul_f32_e32 v33, v33, v37
	v_mul_f32_e32 v33, v33, v40
	v_cvt_pk_bf16_f32 v33, v36, v33
	v_mul_f32_e32 v36, v236, v38
	v_add_f32_e32 v38, v36, v36
	v_cmp_nlt_f32_e32 vcc, s95, v38
	s_and_saveexec_b64 s[34:35], vcc
	s_xor_b64 s[36:37], exec, s[34:35]
	v_mul_f32_e32 v37, 0x3fb8aa3b, v38
	v_exp_f32_e32 v37, v37
	s_nop 0
	v_sub_f32_e32 v37, 1.0, v37
	s_andn2_saveexec_b64 s[36:37], s[36:37]
	v_fma_f32 v37, v38, 0.5, 1.0
	v_mul_f32_e64 v37, v37, -v38
	s_or_b64 exec, exec, s[36:37]
	v_add_f32_e32 v34, v34, v232
	v_mul_f32_e32 v34, 0xbfb8aa3b, v34
	v_exp_f32_e32 v34, v34
	v_add_f32_e32 v38, v39, v229
	v_mul_f32_e32 v38, 0xbfb8aa3b, v38
	v_exp_f32_e32 v38, v38
	v_max_f32_e32 v37, v37, v37
	v_add_f32_e32 v34, 1.0, v34
	v_max_f32_e32 v37, 0, v37
	v_rcp_f32_e32 v34, v34
	v_sqrt_f32_e32 v37, v37
	v_add_f32_e32 v38, 1.0, v38
	v_rcp_f32_e32 v38, v38
	v_lshlrev_b32_e32 v39, 16, v243
	v_mul_f32_e32 v34, v34, v37
	v_mul_f32_e32 v34, v34, v39
	v_cvt_pk_bf16_f32 v34, v36, v34
	v_mul_f32_e32 v36, v237, v38
	v_add_f32_e32 v38, v36, v36
	v_cmp_nlt_f32_e32 vcc, s95, v38
	s_and_saveexec_b64 s[34:35], vcc
	s_xor_b64 s[36:37], exec, s[34:35]
	v_mul_f32_e32 v37, 0x3fb8aa3b, v38
	v_exp_f32_e32 v37, v37
	s_nop 0
	v_sub_f32_e32 v37, 1.0, v37
	s_andn2_saveexec_b64 s[36:37], s[36:37]
	v_fma_f32 v37, v38, 0.5, 1.0
	v_mul_f32_e64 v37, v37, -v38
	s_or_b64 exec, exec, s[36:37]
	v_add_f32_e32 v35, v35, v233
	v_mul_f32_e32 v35, 0xbfb8aa3b, v35
	v_exp_f32_e32 v35, v35
	v_max_f32_e32 v37, v37, v37
	v_max_f32_e32 v37, 0, v37
	v_sqrt_f32_e32 v37, v37
	v_add_f32_e32 v35, 1.0, v35
	v_rcp_f32_e32 v35, v35
	v_and_b32_e32 v38, 0xffff0000, v243
	v_mul_f32_e32 v35, v35, v37
	v_mul_f32_e32 v35, v35, v38
	v_cvt_pk_bf16_f32 v35, v36, v35
	v_mov_b64_e32 v[36:37], s[62:63]
	v_mad_i64_i32 v[36:37], s[34:35], v193, s87, v[36:37]
	v_lshl_add_u64 v[36:37], v[146:147], 2, v[36:37]
	global_store_dwordx4 v[36:37], v[32:35], off offset:64
.LBB0_975:
	s_or_b64 exec, exec, s[22:23]
	s_and_saveexec_b64 s[22:23], s[48:49]
	s_cbranch_execnz .LBB0_979
	s_or_b64 exec, exec, s[22:23]
	s_and_saveexec_b64 s[22:23], s[50:51]
	s_cbranch_execnz .LBB0_996

; __device__ __forceinline__ unsigned cvt_pk_bf16(float lo, float hi) { unsigned r; asm volatile("v_cvt_pk_bf16_f32 %0, %1, %2" : "=v"(r) : "v"(lo), "v"(hi)); return r; }
; __device__ __forceinline__ float bflo(unsigned w) { return __uint_as_float(w << 16); }
; __device__ __forceinline__ float bfhi(unsigned w) { return __uint_as_float(w & 0xffff0000u); }
; __device__ __forceinline__ float fsigmoid(float x) { return __builtin_amdgcn_rcpf(1.0f + __expf(-x)); }
;     __device__ __forceinline__ void operator()(const f32x4 (&acc)[2][2][4][2], const Unit& u, int wr, int wc, int fr, int fq) const {
;     ...
;                 for (int m = 0; m < 4; ++m) { const int row = row0 + ai * 128 + m * 16;
;                     if (row < TT) { const size_t off = (size_t)row * DRNN + ch0 + 16 * n; const u32x2 xw = xq[m]; const f32x4 xc = (f32x4){bflo(xw.x), bfhi(xw.x), bflo(xw.y), bfhi(xw.y)}; u32x4 o;
; #pragma unroll
;                         for (int i = 0; i < 4; ++i) { const float r = fsigmoid(acc[ai][0][m][n][i] + ba[i]), ig = fsigmoid(acc[ai][1][m][n][i] + bx[i]);
;                             const float la = r * lv[i], x2 = la + la, m = x2 > -1e-3f ? -x2 * fmaf(x2, 0.5f, 1.0f) : 1.0f - __expf(x2);
;                             o[i] = cvt_pk_bf16(la, __builtin_amdgcn_sqrtf(fmaxf(m, 0.0f)) * ig * xc[i]); }
;                         *(u32x4*)(AB + off) = o; } }
.LBB0_979:
	v_add_f32_e32 v28, v28, v226
	v_mul_f32_e32 v28, 0xbfb8aa3b, v28
	v_exp_f32_e32 v28, v28
	s_nop 0
	v_add_f32_e32 v28, 1.0, v28
	v_rcp_f32_e32 v28, v28
	s_nop 0
	v_mul_f32_e32 v28, v234, v28
	v_add_f32_e32 v41, v28, v28
	v_cmp_nlt_f32_e32 vcc, s95, v41
	s_and_saveexec_b64 s[34:35], vcc
	s_xor_b64 s[36:37], exec, s[34:35]
	v_mul_f32_e32 v40, 0x3fb8aa3b, v41
	v_exp_f32_e32 v40, v40
	s_nop 0
	v_sub_f32_e32 v40, 1.0, v40
	s_andn2_saveexec_b64 s[36:37], s[36:37]
	v_fma_f32 v40, v41, 0.5, 1.0
	v_mul_f32_e64 v40, v40, -v41
	s_or_b64 exec, exec, s[36:37]
	v_add_f32_e32 v24, v24, v230
	v_mul_f32_e32 v24, 0xbfb8aa3b, v24
	v_exp_f32_e32 v24, v24
	v_add_f32_e32 v29, v29, v227
	v_mul_f32_e32 v29, 0xbfb8aa3b, v29
	v_exp_f32_e32 v29, v29
	v_max_f32_e32 v40, v40, v40
	v_add_f32_e32 v24, 1.0, v24
	v_max_f32_e32 v40, 0, v40
	v_rcp_f32_e32 v24, v24
	v_sqrt_f32_e32 v40, v40
	v_add_f32_e32 v29, 1.0, v29
	v_rcp_f32_e32 v29, v29
	v_lshlrev_b32_e32 v41, 16, v224
	v_mul_f32_e32 v24, v24, v40
	v_mul_f32_e32 v24, v24, v41
	v_cvt_pk_bf16_f32 v24, v28, v24
	v_mul_f32_e32 v28, v235, v29
	v_add_f32_e32 v40, v28, v28
	v_cmp_nlt_f32_e32 vcc, s95, v40
	s_and_saveexec_b64 s[34:35], vcc
	s_xor_b64 s[36:37], exec, s[34:35]
	v_mul_f32_e32 v29, 0x3fb8aa3b, v40
	v_exp_f32_e32 v29, v29
	s_nop 0
	v_sub_f32_e32 v29, 1.0, v29
	s_andn2_saveexec_b64 s[36:37], s[36:37]
	v_fma_f32 v29, v40, 0.5, 1.0
	v_mul_f32_e64 v29, v29, -v40
	s_or_b64 exec, exec, s[36:37]
	v_add_f32_e32 v25, v25, v231
	v_mul_f32_e32 v25, 0xbfb8aa3b, v25
	v_exp_f32_e32 v25, v25
	v_add_f32_e32 v30, v30, v228
	v_mul_f32_e32 v30, 0xbfb8aa3b, v30
	v_exp_f32_e32 v30, v30
	v_max_f32_e32 v29, v29, v29
	v_add_f32_e32 v25, 1.0, v25
	v_max_f32_e32 v29, 0, v29
	v_rcp_f32_e32 v25, v25
	v_sqrt_f32_e32 v29, v29
	v_add_f32_e32 v30, 1.0, v30
	v_rcp_f32_e32 v30, v30
	v_and_b32_e32 v224, 0xffff0000, v224
	v_mul_f32_e32 v25, v25, v29
	v_mul_f32_e32 v25, v25, v224
	v_cvt_pk_bf16_f32 v25, v28, v25
	v_mul_f32_e32 v28, v236, v30
	v_add_f32_e32 v30, v28, v28
	v_cmp_nlt_f32_e32 vcc, s95, v30
	s_and_saveexec_b64 s[34:35], vcc
	s_xor_b64 s[36:37], exec, s[34:35]
	v_mul_f32_e32 v29, 0x3fb8aa3b, v30
	v_exp_f32_e32 v29, v29
	s_nop 0
	v_sub_f32_e32 v29, 1.0, v29
	s_andn2_saveexec_b64 s[36:37], s[36:37]
	v_fma_f32 v29, v30, 0.5, 1.0
	v_mul_f32_e64 v29, v29, -v30
	s_or_b64 exec, exec, s[36:37]
	v_add_f32_e32 v26, v26, v232
	v_mul_f32_e32 v26, 0xbfb8aa3b, v26
	v_exp_f32_e32 v26, v26
	v_add_f32_e32 v30, v31, v229
	v_mul_f32_e32 v30, 0xbfb8aa3b, v30
	v_exp_f32_e32 v30, v30
	v_max_f32_e32 v29, v29, v29
	v_add_f32_e32 v26, 1.0, v26
	v_max_f32_e32 v29, 0, v29
	v_rcp_f32_e32 v26, v26
	v_sqrt_f32_e32 v29, v29
	v_add_f32_e32 v30, 1.0, v30
	v_rcp_f32_e32 v30, v30
	v_lshlrev_b32_e32 v31, 16, v225
	v_mul_f32_e32 v26, v26, v29
	v_mul_f32_e32 v26, v26, v31
	v_cvt_pk_bf16_f32 v26, v28, v26
	v_mul_f32_e32 v28, v237, v30
	v_add_f32_e32 v30, v28, v28
	v_cmp_nlt_f32_e32 vcc, s95, v30
	s_and_saveexec_b64 s[34:35], vcc
	s_xor_b64 s[36:37], exec, s[34:35]
	v_mul_f32_e32 v29, 0x3fb8aa3b, v30
	v_exp_f32_e32 v29, v29
	s_nop 0
	v_sub_f32_e32 v29, 1.0, v29
	s_andn2_saveexec_b64 s[36:37], s[36:37]
	v_fma_f32 v29, v30, 0.5, 1.0
	v_mul_f32_e64 v29, v29, -v30
	s_or_b64 exec, exec, s[36:37]
	v_add_f32_e32 v27, v27, v233
	v_mul_f32_e32 v27, 0xbfb8aa3b, v27
	v_exp_f32_e32 v27, v27
	v_max_f32_e32 v29, v29, v29
	v_max_f32_e32 v29, 0, v29
	v_sqrt_f32_e32 v29, v29
	v_add_f32_e32 v27, 1.0, v27
	v_rcp_f32_e32 v27, v27
	v_and_b32_e32 v30, 0xffff0000, v225
	v_mul_f32_e32 v27, v27, v29
	v_mul_f32_e32 v27, v27, v30
	v_cvt_pk_bf16_f32 v27, v28, v27
	v_mov_b64_e32 v[28:29], s[62:63]
	v_mad_i64_i32 v[28:29], s[34:35], v127, s87, v[28:29]
	v_lshl_add_u64 v[28:29], v[146:147], 2, v[28:29]
	global_store_dwordx4 v[28:29], v[24:27], off offset:64
	s_or_b64 exec, exec, s[22:23]
	s_and_saveexec_b64 s[22:23], s[50:51]
	s_cbranch_execz .LBB0_977
.LBB0_996:
	v_add_f32_e32 v20, v20, v226
	v_mul_f32_e32 v20, 0xbfb8aa3b, v20
	v_exp_f32_e32 v20, v20
	s_nop 0
	v_add_f32_e32 v20, 1.0, v20
	v_rcp_f32_e32 v20, v20
	s_nop 0
	v_mul_f32_e32 v20, v234, v20
	v_add_f32_e32 v25, v20, v20
	v_cmp_nlt_f32_e32 vcc, s95, v25
	s_and_saveexec_b64 s[34:35], vcc
	s_xor_b64 s[36:37], exec, s[34:35]
	v_mul_f32_e32 v24, 0x3fb8aa3b, v25
	v_exp_f32_e32 v24, v24
	s_nop 0
	v_sub_f32_e32 v24, 1.0, v24
	s_andn2_saveexec_b64 s[36:37], s[36:37]
	v_fma_f32 v24, v25, 0.5, 1.0
	v_mul_f32_e64 v24, v24, -v25
	s_or_b64 exec, exec, s[36:37]
	v_add_f32_e32 v16, v16, v230
	v_mul_f32_e32 v16, 0xbfb8aa3b, v16
	v_exp_f32_e32 v16, v16
	v_add_f32_e32 v21, v21, v227
	v_mul_f32_e32 v21, 0xbfb8aa3b, v21
	v_exp_f32_e32 v21, v21
	v_max_f32_e32 v24, v24, v24
	v_add_f32_e32 v16, 1.0, v16
	v_max_f32_e32 v24, 0, v24
	v_rcp_f32_e32 v16, v16
	v_sqrt_f32_e32 v24, v24
	v_add_f32_e32 v21, 1.0, v21
	v_rcp_f32_e32 v21, v21
	v_lshlrev_b32_e32 v25, 16, v208
	v_mul_f32_e32 v16, v16, v24
	v_mul_f32_e32 v16, v16, v25
	v_cvt_pk_bf16_f32 v16, v20, v16
	v_mul_f32_e32 v20, v235, v21
	v_add_f32_e32 v24, v20, v20
	v_cmp_nlt_f32_e32 vcc, s95, v24
	s_and_saveexec_b64 s[34:35], vcc
	s_xor_b64 s[36:37], exec, s[34:35]
	v_mul_f32_e32 v21, 0x3fb8aa3b, v24
	v_exp_f32_e32 v21, v21
	s_nop 0
	v_sub_f32_e32 v21, 1.0, v21
	s_andn2_saveexec_b64 s[36:37], s[36:37]
	v_fma_f32 v21, v24, 0.5, 1.0
	v_mul_f32_e64 v21, v21, -v24
	s_or_b64 exec, exec, s[36:37]
	v_add_f32_e32 v17, v17, v231
	v_mul_f32_e32 v17, 0xbfb8aa3b, v17
	v_exp_f32_e32 v17, v17
	v_add_f32_e32 v22, v22, v228
	v_mul_f32_e32 v22, 0xbfb8aa3b, v22
	v_exp_f32_e32 v22, v22
	v_max_f32_e32 v21, v21, v21
	v_add_f32_e32 v17, 1.0, v17
	v_max_f32_e32 v21, 0, v21
	v_rcp_f32_e32 v17, v17
	v_sqrt_f32_e32 v21, v21
	v_add_f32_e32 v22, 1.0, v22
; __device__ __forceinline__ unsigned cvt_pk_bf16(float lo, float hi) { unsigned r; asm volatile("v_cvt_pk_bf16_f32 %0, %1, %2" : "=v"(r) : "v"(lo), "v"(hi)); return r; }
; __device__ __forceinline__ float bflo(unsigned w) { return __uint_as_float(w << 16); }
; __device__ __forceinline__ float bfhi(unsigned w) { return __uint_as_float(w & 0xffff0000u); }
; __device__ __forceinline__ float fsigmoid(float x) { return __builtin_amdgcn_rcpf(1.0f + __expf(-x)); }
;     __device__ __forceinline__ void operator()(const f32x4 (&acc)[2][2][4][2], const Unit& u, int wr, int wc, int fr, int fq) const {
;     ...
;                 for (int m = 0; m < 4; ++m) { const int row = row0 + ai * 128 + m * 16;
;                     if (row < TT) { const size_t off = (size_t)row * DRNN + ch0 + 16 * n; const u32x2 xw = xq[m]; const f32x4 xc = (f32x4){bflo(xw.x), bfhi(xw.x), bflo(xw.y), bfhi(xw.y)}; u32x4 o;
; #pragma unroll
;                         for (int i = 0; i < 4; ++i) { const float r = fsigmoid(acc[ai][0][m][n][i] + ba[i]), ig = fsigmoid(acc[ai][1][m][n][i] + bx[i]);
;                             const float la = r * lv[i], x2 = la + la, m = x2 > -1e-3f ? -x2 * fmaf(x2, 0.5f, 1.0f) : 1.0f - __expf(x2);
;                             o[i] = cvt_pk_bf16(la, __builtin_amdgcn_sqrtf(fmaxf(m, 0.0f)) * ig * xc[i]); }
;                         *(u32x4*)(AB + off) = o; } }
	v_rcp_f32_e32 v22, v22
	v_and_b32_e32 v24, 0xffff0000, v208
	v_mul_f32_e32 v17, v17, v21
	v_mul_f32_e32 v17, v17, v24
	v_cvt_pk_bf16_f32 v17, v20, v17
	v_mul_f32_e32 v20, v236, v22
	v_add_f32_e32 v22, v20, v20
	v_cmp_nlt_f32_e32 vcc, s95, v22
	s_and_saveexec_b64 s[34:35], vcc
	s_xor_b64 s[36:37], exec, s[34:35]
	v_mul_f32_e32 v21, 0x3fb8aa3b, v22
	v_exp_f32_e32 v21, v21
	s_nop 0
	v_sub_f32_e32 v21, 1.0, v21
	s_andn2_saveexec_b64 s[36:37], s[36:37]
	v_fma_f32 v21, v22, 0.5, 1.0
	v_mul_f32_e64 v21, v21, -v22
	s_or_b64 exec, exec, s[36:37]
	v_add_f32_e32 v18, v18, v232
	v_mul_f32_e32 v18, 0xbfb8aa3b, v18
	v_exp_f32_e32 v18, v18
	v_add_f32_e32 v22, v23, v229
	v_mul_f32_e32 v22, 0xbfb8aa3b, v22
	v_exp_f32_e32 v22, v22
	v_max_f32_e32 v21, v21, v21
	v_add_f32_e32 v18, 1.0, v18
	v_max_f32_e32 v21, 0, v21
	v_rcp_f32_e32 v18, v18
	v_sqrt_f32_e32 v21, v21
	v_add_f32_e32 v22, 1.0, v22
	v_rcp_f32_e32 v22, v22
	v_lshlrev_b32_e32 v23, 16, v209
	v_mul_f32_e32 v18, v18, v21
	v_mul_f32_e32 v18, v18, v23
	v_cvt_pk_bf16_f32 v18, v20, v18
	v_mul_f32_e32 v20, v237, v22
	v_add_f32_e32 v22, v20, v20
	v_cmp_nlt_f32_e32 vcc, s95, v22
	s_and_saveexec_b64 s[34:35], vcc
	s_xor_b64 s[36:37], exec, s[34:35]
	v_mul_f32_e32 v21, 0x3fb8aa3b, v22
	v_exp_f32_e32 v21, v21
	s_nop 0
	v_sub_f32_e32 v21, 1.0, v21
	s_andn2_saveexec_b64 s[36:37], s[36:37]
	v_fma_f32 v21, v22, 0.5, 1.0
	v_mul_f32_e64 v21, v21, -v22
	s_or_b64 exec, exec, s[36:37]
	v_add_f32_e32 v19, v19, v233
	v_mul_f32_e32 v19, 0xbfb8aa3b, v19
	v_exp_f32_e32 v19, v19
	v_max_f32_e32 v21, v21, v21
	v_max_f32_e32 v21, 0, v21
	v_sqrt_f32_e32 v21, v21
	v_add_f32_e32 v19, 1.0, v19
	v_rcp_f32_e32 v19, v19
	v_and_b32_e32 v22, 0xffff0000, v209
	v_mul_f32_e32 v19, v19, v21
	v_mul_f32_e32 v19, v19, v22
	v_cvt_pk_bf16_f32 v19, v20, v19
	v_mov_b64_e32 v[20:21], s[62:63]
	v_mad_i64_i32 v[20:21], s[34:35], v126, s87, v[20:21]
	v_lshl_add_u64 v[20:21], v[146:147], 2, v[20:21]
	global_store_dwordx4 v[20:21], v[16:19], off offset:64
	s_or_b64 exec, exec, s[22:23]
	s_and_saveexec_b64 s[22:23], s[52:53]
	s_cbranch_execz .LBB0_978
.LBB0_1013:
	v_add_f32_e32 v12, v12, v226
	v_mul_f32_e32 v12, 0xbfb8aa3b, v12
	v_exp_f32_e32 v12, v12
	s_nop 0
	v_add_f32_e32 v12, 1.0, v12
	v_rcp_f32_e32 v12, v12
	s_nop 0
	v_mul_f32_e32 v12, v234, v12
	v_add_f32_e32 v17, v12, v12
	v_cmp_nlt_f32_e32 vcc, s95, v17
	s_and_saveexec_b64 s[34:35], vcc
	s_xor_b64 s[36:37], exec, s[34:35]
	v_mul_f32_e32 v16, 0x3fb8aa3b, v17
	v_exp_f32_e32 v16, v16
	s_nop 0
	v_sub_f32_e32 v16, 1.0, v16
	s_andn2_saveexec_b64 s[36:37], s[36:37]
	v_fma_f32 v16, v17, 0.5, 1.0
	v_mul_f32_e64 v16, v16, -v17
	s_or_b64 exec, exec, s[36:37]
	v_add_f32_e32 v8, v8, v230
	v_mul_f32_e32 v8, 0xbfb8aa3b, v8
	v_exp_f32_e32 v8, v8
	v_add_f32_e32 v13, v13, v227
	v_mul_f32_e32 v13, 0xbfb8aa3b, v13
	v_exp_f32_e32 v13, v13
	v_max_f32_e32 v16, v16, v16
	v_add_f32_e32 v8, 1.0, v8
	v_max_f32_e32 v16, 0, v16
	v_rcp_f32_e32 v8, v8
	v_sqrt_f32_e32 v16, v16
	v_add_f32_e32 v13, 1.0, v13
	v_rcp_f32_e32 v13, v13
	v_lshlrev_b32_e32 v17, 16, v210
	v_mul_f32_e32 v8, v8, v16
	v_mul_f32_e32 v8, v8, v17
	v_cvt_pk_bf16_f32 v8, v12, v8
	v_mul_f32_e32 v12, v235, v13
	v_add_f32_e32 v16, v12, v12
	v_cmp_nlt_f32_e32 vcc, s95, v16
	s_and_saveexec_b64 s[34:35], vcc
	s_xor_b64 s[36:37], exec, s[34:35]
	v_mul_f32_e32 v13, 0x3fb8aa3b, v16
	v_exp_f32_e32 v13, v13
	s_nop 0
	v_sub_f32_e32 v13, 1.0, v13
	s_andn2_saveexec_b64 s[36:37], s[36:37]
	v_fma_f32 v13, v16, 0.5, 1.0
	v_mul_f32_e64 v13, v13, -v16
	s_or_b64 exec, exec, s[36:37]
	v_add_f32_e32 v9, v9, v231
	v_mul_f32_e32 v9, 0xbfb8aa3b, v9
	v_exp_f32_e32 v9, v9
	v_add_f32_e32 v14, v14, v228
	v_mul_f32_e32 v14, 0xbfb8aa3b, v14
	v_exp_f32_e32 v14, v14
	v_max_f32_e32 v13, v13, v13
	v_add_f32_e32 v9, 1.0, v9
	v_max_f32_e32 v13, 0, v13
	v_rcp_f32_e32 v9, v9
	v_sqrt_f32_e32 v13, v13
	v_add_f32_e32 v14, 1.0, v14
	v_rcp_f32_e32 v14, v14
	v_and_b32_e32 v16, 0xffff0000, v210
	v_mul_f32_e32 v9, v9, v13
	v_mul_f32_e32 v9, v9, v16
	v_cvt_pk_bf16_f32 v9, v12, v9
	v_mul_f32_e32 v12, v236, v14
	v_add_f32_e32 v14, v12, v12
	v_cmp_nlt_f32_e32 vcc, s95, v14
	s_and_saveexec_b64 s[34:35], vcc
	s_xor_b64 s[36:37], exec, s[34:35]
	v_mul_f32_e32 v13, 0x3fb8aa3b, v14
	v_exp_f32_e32 v13, v13
	s_nop 0
	v_sub_f32_e32 v13, 1.0, v13
	s_andn2_saveexec_b64 s[36:37], s[36:37]
	v_fma_f32 v13, v14, 0.5, 1.0
	v_mul_f32_e64 v13, v13, -v14
	s_or_b64 exec, exec, s[36:37]
	v_add_f32_e32 v10, v10, v232
	v_mul_f32_e32 v10, 0xbfb8aa3b, v10
	v_exp_f32_e32 v10, v10
	v_add_f32_e32 v14, v15, v229
	v_mul_f32_e32 v14, 0xbfb8aa3b, v14
	v_exp_f32_e32 v14, v14
	v_max_f32_e32 v13, v13, v13
	v_add_f32_e32 v10, 1.0, v10
	v_max_f32_e32 v13, 0, v13
	v_rcp_f32_e32 v10, v10
	v_sqrt_f32_e32 v13, v13
	v_add_f32_e32 v14, 1.0, v14
	v_rcp_f32_e32 v14, v14
	v_lshlrev_b32_e32 v15, 16, v211
	v_mul_f32_e32 v10, v10, v13
	v_mul_f32_e32 v10, v10, v15
	v_cvt_pk_bf16_f32 v10, v12, v10
	v_mul_f32_e32 v12, v237, v14
	v_add_f32_e32 v14, v12, v12
	v_cmp_nlt_f32_e32 vcc, s95, v14
	s_and_saveexec_b64 s[34:35], vcc
	s_xor_b64 s[36:37], exec, s[34:35]
	v_mul_f32_e32 v13, 0x3fb8aa3b, v14
	v_exp_f32_e32 v13, v13
	s_nop 0
	v_sub_f32_e32 v13, 1.0, v13
	s_andn2_saveexec_b64 s[36:37], s[36:37]
	v_fma_f32 v13, v14, 0.5, 1.0
	v_mul_f32_e64 v13, v13, -v14
	s_or_b64 exec, exec, s[36:37]
	v_add_f32_e32 v11, v11, v233
	v_mul_f32_e32 v11, 0xbfb8aa3b, v11
	v_exp_f32_e32 v11, v11
	v_max_f32_e32 v13, v13, v13
	v_max_f32_e32 v13, 0, v13
	v_sqrt_f32_e32 v13, v13
	v_add_f32_e32 v11, 1.0, v11
	v_rcp_f32_e32 v11, v11
	v_and_b32_e32 v14, 0xffff0000, v211
	v_mul_f32_e32 v11, v11, v13
	v_mul_f32_e32 v11, v11, v14
	v_cvt_pk_bf16_f32 v11, v12, v11
	v_mov_b64_e32 v[12:13], s[62:63]
	v_mad_i64_i32 v[12:13], s[34:35], v125, s87, v[12:13]
	v_lshl_add_u64 v[12:13], v[146:147], 2, v[12:13]
	global_store_dwordx4 v[12:13], v[8:11], off offset:64
	s_or_b64 exec, exec, s[22:23]
	s_and_saveexec_b64 s[22:23], s[54:55]
	s_cbranch_execz .LBB0_1047
; __device__ __forceinline__ unsigned cvt_pk_bf16(float lo, float hi) { unsigned r; asm volatile("v_cvt_pk_bf16_f32 %0, %1, %2" : "=v"(r) : "v"(lo), "v"(hi)); return r; }
; __device__ __forceinline__ float bflo(unsigned w) { return __uint_as_float(w << 16); }
; __device__ __forceinline__ float bfhi(unsigned w) { return __uint_as_float(w & 0xffff0000u); }
; __device__ __forceinline__ float fsigmoid(float x) { return __builtin_amdgcn_rcpf(1.0f + __expf(-x)); }
;     __device__ __forceinline__ void operator()(const f32x4 (&acc)[2][2][4][2], const Unit& u, int wr, int wc, int fr, int fq) const {
;     ...
;                 for (int m = 0; m < 4; ++m) { const int row = row0 + ai * 128 + m * 16;
;                     if (row < TT) { const size_t off = (size_t)row * DRNN + ch0 + 16 * n; const u32x2 xw = xq[m]; const f32x4 xc = (f32x4){bflo(xw.x), bfhi(xw.x), bflo(xw.y), bfhi(xw.y)}; u32x4 o;
; #pragma unroll
;                         for (int i = 0; i < 4; ++i) { const float r = fsigmoid(acc[ai][0][m][n][i] + ba[i]), ig = fsigmoid(acc[ai][1][m][n][i] + bx[i]);
;                             const float la = r * lv[i], x2 = la + la, m = x2 > -1e-3f ? -x2 * fmaf(x2, 0.5f, 1.0f) : 1.0f - __expf(x2);
;                             o[i] = cvt_pk_bf16(la, __builtin_amdgcn_sqrtf(fmaxf(m, 0.0f)) * ig * xc[i]); }
;                         *(u32x4*)(AB + off) = o; } }
.LBB0_1030:
	v_add_f32_e32 v4, v4, v226
	v_mul_f32_e32 v4, 0xbfb8aa3b, v4
	v_exp_f32_e32 v4, v4
	s_nop 0
	v_add_f32_e32 v4, 1.0, v4
	v_rcp_f32_e32 v4, v4
	s_nop 0
	v_mul_f32_e32 v4, v234, v4
	v_add_f32_e32 v9, v4, v4
	v_cmp_nlt_f32_e32 vcc, s95, v9
	s_and_saveexec_b64 s[34:35], vcc
	s_xor_b64 s[36:37], exec, s[34:35]
	v_mul_f32_e32 v8, 0x3fb8aa3b, v9
	v_exp_f32_e32 v8, v8
	s_nop 0
	v_sub_f32_e32 v8, 1.0, v8
	s_andn2_saveexec_b64 s[36:37], s[36:37]
	v_fma_f32 v8, v9, 0.5, 1.0
	v_mul_f32_e64 v8, v8, -v9
	s_or_b64 exec, exec, s[36:37]
	v_add_f32_e32 v0, v0, v230
	v_mul_f32_e32 v0, 0xbfb8aa3b, v0
	v_exp_f32_e32 v0, v0
	v_max_f32_e32 v8, v8, v8
	v_max_f32_e32 v8, 0, v8
	v_sqrt_f32_e32 v8, v8
	v_add_f32_e32 v0, 1.0, v0
	v_rcp_f32_e32 v0, v0
	v_lshlrev_b32_e32 v9, 16, v212
	v_mul_f32_e32 v0, v0, v8
	v_mul_f32_e32 v0, v0, v9
	v_cvt_pk_bf16_f32 v0, v4, v0
	v_add_f32_e32 v4, v5, v227
	v_mul_f32_e32 v4, 0xbfb8aa3b, v4
	v_exp_f32_e32 v4, v4
	s_nop 0
	v_add_f32_e32 v4, 1.0, v4
	v_rcp_f32_e32 v4, v4
	s_nop 0
	v_mul_f32_e32 v4, v235, v4
	v_add_f32_e32 v8, v4, v4
	v_cmp_nlt_f32_e32 vcc, s95, v8
	s_and_saveexec_b64 s[34:35], vcc
	s_xor_b64 s[36:37], exec, s[34:35]
	v_mul_f32_e32 v5, 0x3fb8aa3b, v8
	v_exp_f32_e32 v5, v5
	s_nop 0
	v_sub_f32_e32 v5, 1.0, v5
	s_andn2_saveexec_b64 s[36:37], s[36:37]
	v_fma_f32 v5, v8, 0.5, 1.0
	v_mul_f32_e64 v5, v5, -v8
	s_or_b64 exec, exec, s[36:37]
	v_add_f32_e32 v1, v1, v231
	v_mul_f32_e32 v1, 0xbfb8aa3b, v1
	v_exp_f32_e32 v1, v1
	v_add_f32_e32 v6, v6, v228
	v_mul_f32_e32 v6, 0xbfb8aa3b, v6
	v_exp_f32_e32 v6, v6
	v_max_f32_e32 v5, v5, v5
	v_add_f32_e32 v1, 1.0, v1
	v_max_f32_e32 v5, 0, v5
	v_rcp_f32_e32 v1, v1
	v_sqrt_f32_e32 v5, v5
	v_add_f32_e32 v6, 1.0, v6
	v_rcp_f32_e32 v6, v6
	v_and_b32_e32 v8, 0xffff0000, v212
	v_mul_f32_e32 v1, v1, v5
	v_mul_f32_e32 v1, v1, v8
	v_cvt_pk_bf16_f32 v1, v4, v1
	v_mul_f32_e32 v4, v236, v6
	v_add_f32_e32 v6, v4, v4
	v_cmp_nlt_f32_e32 vcc, s95, v6
	s_and_saveexec_b64 s[34:35], vcc
	s_xor_b64 s[36:37], exec, s[34:35]
	v_mul_f32_e32 v5, 0x3fb8aa3b, v6
	v_exp_f32_e32 v5, v5
	s_nop 0
	v_sub_f32_e32 v5, 1.0, v5
	s_andn2_saveexec_b64 s[36:37], s[36:37]
	v_fma_f32 v5, v6, 0.5, 1.0
	v_mul_f32_e64 v5, v5, -v6
	s_or_b64 exec, exec, s[36:37]
	v_add_f32_e32 v2, v2, v232
	v_mul_f32_e32 v2, 0xbfb8aa3b, v2
	v_exp_f32_e32 v2, v2
	v_add_f32_e32 v6, v7, v229
	v_mul_f32_e32 v6, 0xbfb8aa3b, v6
	v_exp_f32_e32 v6, v6
	v_max_f32_e32 v5, v5, v5
	v_add_f32_e32 v2, 1.0, v2
	v_max_f32_e32 v5, 0, v5
	v_rcp_f32_e32 v2, v2
	v_sqrt_f32_e32 v5, v5
	v_add_f32_e32 v6, 1.0, v6
	v_rcp_f32_e32 v6, v6
	v_lshlrev_b32_e32 v7, 16, v213
	v_mul_f32_e32 v2, v2, v5
	v_mul_f32_e32 v2, v2, v7
	v_cvt_pk_bf16_f32 v2, v4, v2
	v_mul_f32_e32 v4, v237, v6
	v_add_f32_e32 v6, v4, v4
	v_cmp_nlt_f32_e32 vcc, s95, v6
	s_and_saveexec_b64 s[34:35], vcc
	s_xor_b64 s[36:37], exec, s[34:35]
	v_mul_f32_e32 v5, 0x3fb8aa3b, v6
	v_exp_f32_e32 v5, v5
	s_nop 0
	v_sub_f32_e32 v5, 1.0, v5
	s_andn2_saveexec_b64 s[36:37], s[36:37]
	v_fma_f32 v5, v6, 0.5, 1.0
	v_mul_f32_e64 v5, v5, -v6
	s_or_b64 exec, exec, s[36:37]
	v_add_f32_e32 v3, v3, v233
	v_mul_f32_e32 v3, 0xbfb8aa3b, v3
	v_exp_f32_e32 v3, v3
	v_max_f32_e32 v5, v5, v5
	v_max_f32_e32 v5, 0, v5
	v_sqrt_f32_e32 v5, v5
	v_add_f32_e32 v3, 1.0, v3
	v_rcp_f32_e32 v3, v3
	v_and_b32_e32 v6, 0xffff0000, v213
	v_mul_f32_e32 v3, v3, v5
	v_mul_f32_e32 v3, v3, v6
	v_cvt_pk_bf16_f32 v3, v4, v3
	v_mov_b64_e32 v[4:5], s[62:63]
	v_mad_i64_i32 v[4:5], s[34:35], v124, s87, v[4:5]
	v_lshl_add_u64 v[4:5], v[146:147], 2, v[4:5]
	global_store_dwordx4 v[4:5], v[0:3], off offset:64
